# static priority: all per-segment s_setprio flips deleted, one s_setprio 1 for waves 4-7 at each K-loop entry, s_setprio 0 after the loop
# baseline (speedup 1.0000x reference)
; #define PG8_STAGE(bufoff, gbase, voff) do { _Pragma("unroll") for (int _i = 0; _i < 2; ++_i) \
;         __builtin_amdgcn_global_load_lds((const unsigned*)((const char*)(gbase) + (voff)[_i]), (PG8_LAS unsigned*)(lds + (bufoff) + ldsw + _i * 8192), 16, 0, 0); } while (0)
; #define PG8_LDA(dst, b, h) do { _Pragma("unroll") for (int m = 0; m < 4; ++m) _Pragma("unroll") for (int k = 0; k < 2; ++k) dst[m][k] = *(const PG8_LAS bf16x8*)(lds + PG8_SA(b, h) + aoff + m * 2048 + k * 1024); } while (0)
; #define PG8_LDB(dst, b, h) do { _Pragma("unroll") for (int n = 0; n < 2; ++n) _Pragma("unroll") for (int k = 0; k < 2; ++k) dst[n][k] = *(const PG8_LAS bf16x8*)(lds + PG8_SB(b, h) + boff + n * 2048 + k * 1024); } while (0)
; #define PG8_MMA(ai, bj, At, Bt) do { __builtin_amdgcn_s_setprio(1); _Pragma("unroll") for (int m = 0; m < 4; ++m) _Pragma("unroll") for (int n = 0; n < 2; ++n) _Pragma("unroll") for (int k = 0; k < 2; ++k) \
;         acc[ai][bj][m][n] = __builtin_amdgcn_mfma_f32_16x16x32_bf16(Bt[n][k], At[m][k], acc[ai][bj][m][n], 0, 0, 0); __builtin_amdgcn_s_setprio(0); } while (0)
; #define PG8_WAIT_V(n) asm volatile("s_waitcnt vmcnt(" #n ")" ::: "memory")
; #define PG8_WAIT_L(n) asm volatile("s_waitcnt lgkmcnt(" #n ")" ::: "memory")
; #define PG8_BAR __builtin_amdgcn_s_barrier()
; #define PG8_SCHED __builtin_amdgcn_sched_barrier(0)
; template <class Epi, class Sched, bool ALIGN_EPI = false, bool SP2 = false>
; __device__ __forceinline__ void gemm_phase(PG8_LAS unsigned char* lds, const Gemm g, const Sched& S, const Epi& E) {
;     ...
;     f32x4 acc[2][2][4][2];
; #pragma unroll
;     for (int a = 0; a < 2; ++a)
; #pragma unroll
;         for (int b = 0; b < 2; ++b)
; #pragma unroll
;             for (int m = 0; m < 4; ++m)
; #pragma unroll
;                 for (int n = 0; n < 2; ++n) acc[a][b][m][n] = (f32x4){0.f, 0.f, 0.f, 0.f};
;     ...
;             PG8_LDB(B0, 0, 0); PG8_LDB(B1, 0, 1); PG8_SCHED; PG8_LDA(At, 0, 0); PG8_STAGE(PG8_SA(1, 1), a1 + hstep, voffA);
;             PG8_WAIT_V(8); PG8_WAIT_L(0); PG8_BAR; PG8_MMA(0, 0, At, B0); PG8_MMA(0, 1, At, B1); PG8_BAR; PG8_SCHED;
.LBB0_109:
	s_ashr_i32 s17, s16, 31
	s_lshl_b64 s[18:19], s[16:17], 19
	s_add_u32 s18, s30, s18
	s_addc_u32 s19, s31, s19
	s_and_b64 s[42:43], s[4:5], exec
	s_cselect_b32 s17, s19, s45
	s_cselect_b32 s62, s18, s44
	s_ashr_i32 s15, s14, 31
	s_lshl_b64 s[42:43], s[14:15], 19
	s_add_u32 s42, s20, s42
	s_addc_u32 s43, s38, s43
	s_and_b64 s[48:49], s[4:5], exec
	s_cselect_b32 s15, s43, s47
	s_cselect_b32 s63, s42, s46
	s_add_u32 s44, s44, 0x40080
	s_addc_u32 s45, s45, 0
	s_add_u32 s64, s46, 0x100
	v_mov_b32_e32 v0, 0
	s_addc_u32 s65, s47, 0
	s_mov_b32 s66, -2
	v_mov_b32_e32 v1, v0
	v_mov_b32_e32 v2, v0
	v_mov_b32_e32 v3, v0
	v_mov_b32_e32 v8, v0
	v_mov_b32_e32 v9, v0
	v_mov_b32_e32 v10, v0
	v_mov_b32_e32 v11, v0
	v_mov_b32_e32 v16, v0
	v_mov_b32_e32 v17, v0
	v_mov_b32_e32 v18, v0
	v_mov_b32_e32 v19, v0
	v_mov_b32_e32 v24, v0
	v_mov_b32_e32 v25, v0
	v_mov_b32_e32 v26, v0
	v_mov_b32_e32 v27, v0
	v_mov_b32_e32 v32, v0
	v_mov_b32_e32 v33, v0
	v_mov_b32_e32 v34, v0
	v_mov_b32_e32 v35, v0
	v_mov_b32_e32 v40, v0
	v_mov_b32_e32 v41, v0
	v_mov_b32_e32 v42, v0
	v_mov_b32_e32 v43, v0
	v_mov_b32_e32 v48, v0
	v_mov_b32_e32 v49, v0
	v_mov_b32_e32 v50, v0
	v_mov_b32_e32 v51, v0
	v_mov_b32_e32 v56, v0
	v_mov_b32_e32 v57, v0
	v_mov_b32_e32 v58, v0
	v_mov_b32_e32 v59, v0
	v_mov_b32_e32 v4, v0
	v_mov_b32_e32 v5, v0
	v_mov_b32_e32 v6, v0
	v_mov_b32_e32 v7, v0
	v_mov_b32_e32 v12, v0
	v_mov_b32_e32 v13, v0
	v_mov_b32_e32 v14, v0
	v_mov_b32_e32 v15, v0
	v_mov_b32_e32 v20, v0
	v_mov_b32_e32 v21, v0
	v_mov_b32_e32 v22, v0
	v_mov_b32_e32 v23, v0
	v_mov_b32_e32 v28, v0
	v_mov_b32_e32 v29, v0
	v_mov_b32_e32 v30, v0
	v_mov_b32_e32 v31, v0
	v_mov_b32_e32 v36, v0
	v_mov_b32_e32 v37, v0
	v_mov_b32_e32 v38, v0
	v_mov_b32_e32 v39, v0
	v_mov_b32_e32 v44, v0
	v_mov_b32_e32 v45, v0
	v_mov_b32_e32 v46, v0
	v_mov_b32_e32 v47, v0
	v_mov_b32_e32 v52, v0
	v_mov_b32_e32 v53, v0
	v_mov_b32_e32 v54, v0
	v_mov_b32_e32 v55, v0
	v_mov_b32_e32 v60, v0
	v_mov_b32_e32 v61, v0
	v_mov_b32_e32 v62, v0
	v_mov_b32_e32 v63, v0
	v_mov_b32_e32 v64, v0
	v_mov_b32_e32 v65, v0
	v_mov_b32_e32 v66, v0
	v_mov_b32_e32 v67, v0
	v_mov_b32_e32 v72, v0
	v_mov_b32_e32 v73, v0
	v_mov_b32_e32 v74, v0
	v_mov_b32_e32 v75, v0
	v_mov_b32_e32 v82, v0
	v_mov_b32_e32 v83, v0
	v_mov_b32_e32 v84, v0
	v_mov_b32_e32 v85, v0
	v_mov_b32_e32 v90, v0
	v_mov_b32_e32 v91, v0
	v_mov_b32_e32 v92, v0
	v_mov_b32_e32 v93, v0
	v_mov_b32_e32 v98, v0
	v_mov_b32_e32 v99, v0
	v_mov_b32_e32 v100, v0
	v_mov_b32_e32 v101, v0
	v_mov_b32_e32 v106, v0
	v_mov_b32_e32 v107, v0
	v_mov_b32_e32 v108, v0
	v_mov_b32_e32 v109, v0
	v_mov_b32_e32 v114, v0
	v_mov_b32_e32 v115, v0
	v_mov_b32_e32 v116, v0
	v_mov_b32_e32 v117, v0
	v_mov_b32_e32 v122, v0
	v_mov_b32_e32 v123, v0
	v_mov_b32_e32 v124, v0
	v_mov_b32_e32 v125, v0
	v_mov_b32_e32 v68, v0
	v_mov_b32_e32 v69, v0
	v_mov_b32_e32 v70, v0
	v_mov_b32_e32 v71, v0
	v_mov_b32_e32 v76, v0
	v_mov_b32_e32 v77, v0
	v_mov_b32_e32 v78, v0
	v_mov_b32_e32 v79, v0
	v_mov_b32_e32 v86, v0
	v_mov_b32_e32 v87, v0
	v_mov_b32_e32 v88, v0
	v_mov_b32_e32 v89, v0
	v_mov_b32_e32 v94, v0
	v_mov_b32_e32 v95, v0
	v_mov_b32_e32 v96, v0
	v_mov_b32_e32 v97, v0
	v_mov_b32_e32 v102, v0
	v_mov_b32_e32 v103, v0
	v_mov_b32_e32 v104, v0
	v_mov_b32_e32 v105, v0
	v_mov_b32_e32 v110, v0
	v_mov_b32_e32 v111, v0
	v_mov_b32_e32 v112, v0
	v_mov_b32_e32 v113, v0
	v_mov_b32_e32 v118, v0
	v_mov_b32_e32 v119, v0
	v_mov_b32_e32 v120, v0
	v_mov_b32_e32 v121, v0
	v_mov_b32_e32 v126, v0
	v_mov_b32_e32 v127, v0
	v_mov_b32_e32 v128, v0
	v_mov_b32_e32 v129, v0
	v_readfirstlane_b32 s100, v202
	s_nop 3
	s_lshr_b32 s100, s100, 8
	s_cmp_eq_u32 s100, 0
	s_cbranch_scc1 .Lsp_ffn
	s_setprio 1
.Lsp_ffn:
.LBB0_110:
	s_add_u32 s46, s44, 0xfffc0080
	s_addc_u32 s47, s45, -1
	s_add_i32 s67, 0, 0x10000
	s_cmp_eq_u32 s66, 12
	s_cselect_b32 s49, s17, s47
	s_cselect_b32 s48, s62, s46
	v_add_u32_e32 v145, s67, v143
	s_cselect_b32 s47, s15, s65
	s_cselect_b32 s46, s63, s64
	s_add_i32 s70, 0, 0x14000
	ds_read_b128 v[146:149], v145
	ds_read_b128 v[150:153], v145 offset:1024
	ds_read_b128 v[154:157], v145 offset:2048
	ds_read_b128 v[158:161], v145 offset:3072
	v_add_u32_e32 v145, s70, v143
	ds_read_b128 v[176:179], v145
	ds_read_b128 v[180:183], v145 offset:1024
	ds_read_b128 v[184:187], v145 offset:2048
	ds_read_b128 v[188:191], v145 offset:3072
	v_lshl_add_u64 v[200:201], s[44:45], 0, v[138:139]
	s_add_i32 m0, s50, 0xc000
	ds_read_b128 v[192:195], v144
	ds_read_b128 v[196:199], v144 offset:1024
	ds_read_b128 v[208:211], v144 offset:2048
	ds_read_b128 v[212:215], v144 offset:3072
	ds_read_b128 v[216:219], v144 offset:4096
	ds_read_b128 v[220:223], v144 offset:5120
	ds_read_b128 v[224:227], v144 offset:6144
	ds_read_b128 v[228:231], v144 offset:7168
	global_load_lds_dwordx4 v[200:201], off
	v_lshl_add_u64 v[200:201], s[44:45], 0, v[140:141]
	s_add_i32 m0, s50, 0xe000
	s_nop 0
	global_load_lds_dwordx4 v[200:201], off
	s_waitcnt vmcnt(8)
	s_waitcnt lgkmcnt(0)
	s_barrier
; #define PG8_STAGE(bufoff, gbase, voff) do { _Pragma("unroll") for (int _i = 0; _i < 2; ++_i) \
;         __builtin_amdgcn_global_load_lds((const unsigned*)((const char*)(gbase) + (voff)[_i]), (PG8_LAS unsigned*)(lds + (bufoff) + ldsw + _i * 8192), 16, 0, 0); } while (0)
; #define PG8_LDA(dst, b, h) do { _Pragma("unroll") for (int m = 0; m < 4; ++m) _Pragma("unroll") for (int k = 0; k < 2; ++k) dst[m][k] = *(const PG8_LAS bf16x8*)(lds + PG8_SA(b, h) + aoff + m * 2048 + k * 1024); } while (0)
; #define PG8_MMA(ai, bj, At, Bt) do { __builtin_amdgcn_s_setprio(1); _Pragma("unroll") for (int m = 0; m < 4; ++m) _Pragma("unroll") for (int n = 0; n < 2; ++n) _Pragma("unroll") for (int k = 0; k < 2; ++k) \
;         acc[ai][bj][m][n] = __builtin_amdgcn_mfma_f32_16x16x32_bf16(Bt[n][k], At[m][k], acc[ai][bj][m][n], 0, 0, 0); __builtin_amdgcn_s_setprio(0); } while (0)
; #define PG8_WAIT_V(n) asm volatile("s_waitcnt vmcnt(" #n ")" ::: "memory")
; #define PG8_WAIT_L(n) asm volatile("s_waitcnt lgkmcnt(" #n ")" ::: "memory")
; #define PG8_BAR __builtin_amdgcn_s_barrier()
; #define PG8_SCHED __builtin_amdgcn_sched_barrier(0)
; template <class Epi, class Sched, bool ALIGN_EPI = false, bool SP2 = false>
; __device__ __forceinline__ void gemm_phase(PG8_LAS unsigned char* lds, const Gemm g, const Sched& S, const Epi& E) {
;     ...
;             PG8_WAIT_V(8); PG8_WAIT_L(0); PG8_BAR; PG8_MMA(0, 0, At, B0); PG8_MMA(0, 1, At, B1); PG8_BAR; PG8_SCHED;
;             PG8_LDA(At, 0, 1); PG8_STAGE(PG8_SB(0, 0), b2, voffB); PG8_STAGE(PG8_SB(0, 1), b2 + hstep, voffB); PG8_STAGE(PG8_SA(0, 0), a2, voffA);
;             PG8_WAIT_V(8); PG8_WAIT_L(0); PG8_BAR; PG8_MMA(1, 0, At, B0); PG8_MMA(1, 1, At, B1); PG8_BAR; PG8_SCHED;
	v_mfma_f32_16x16x32_bf16 v[126:129], v[146:149], v[192:195], v[126:129]
	v_mfma_f32_16x16x32_bf16 v[118:121], v[154:157], v[192:195], v[118:121]
	v_mfma_f32_16x16x32_bf16 v[110:113], v[146:149], v[208:211], v[110:113]
	v_mfma_f32_16x16x32_bf16 v[102:105], v[154:157], v[208:211], v[102:105]
	v_mfma_f32_16x16x32_bf16 v[94:97], v[146:149], v[216:219], v[94:97]
	v_mfma_f32_16x16x32_bf16 v[86:89], v[154:157], v[216:219], v[86:89]
	v_mfma_f32_16x16x32_bf16 v[76:79], v[146:149], v[224:227], v[76:79]
	v_mfma_f32_16x16x32_bf16 v[68:71], v[154:157], v[224:227], v[68:71]
	v_mfma_f32_16x16x32_bf16 v[126:129], v[150:153], v[196:199], v[126:129]
	v_mfma_f32_16x16x32_bf16 v[118:121], v[158:161], v[196:199], v[118:121]
	v_mfma_f32_16x16x32_bf16 v[110:113], v[150:153], v[212:215], v[110:113]
	v_mfma_f32_16x16x32_bf16 v[102:105], v[158:161], v[212:215], v[102:105]
	v_mfma_f32_16x16x32_bf16 v[94:97], v[150:153], v[220:223], v[94:97]
	v_mfma_f32_16x16x32_bf16 v[86:89], v[158:161], v[220:223], v[86:89]
	v_mfma_f32_16x16x32_bf16 v[76:79], v[150:153], v[228:231], v[76:79]
	v_mfma_f32_16x16x32_bf16 v[68:71], v[158:161], v[228:231], v[68:71]
	v_mfma_f32_16x16x32_bf16 v[122:125], v[176:179], v[192:195], v[122:125]
	v_mfma_f32_16x16x32_bf16 v[114:117], v[184:187], v[192:195], v[114:117]
	v_mfma_f32_16x16x32_bf16 v[106:109], v[176:179], v[208:211], v[106:109]
	v_mfma_f32_16x16x32_bf16 v[98:101], v[184:187], v[208:211], v[98:101]
	v_mfma_f32_16x16x32_bf16 v[90:93], v[176:179], v[216:219], v[90:93]
	v_mfma_f32_16x16x32_bf16 v[82:85], v[184:187], v[216:219], v[82:85]
	v_mfma_f32_16x16x32_bf16 v[72:75], v[176:179], v[224:227], v[72:75]
	v_mfma_f32_16x16x32_bf16 v[64:67], v[184:187], v[224:227], v[64:67]
	v_mfma_f32_16x16x32_bf16 v[122:125], v[180:183], v[196:199], v[122:125]
	v_mfma_f32_16x16x32_bf16 v[114:117], v[188:191], v[196:199], v[114:117]
	v_mfma_f32_16x16x32_bf16 v[106:109], v[180:183], v[212:215], v[106:109]
	v_mfma_f32_16x16x32_bf16 v[98:101], v[188:191], v[212:215], v[98:101]
	v_mfma_f32_16x16x32_bf16 v[90:93], v[180:183], v[220:223], v[90:93]
	v_mfma_f32_16x16x32_bf16 v[82:85], v[188:191], v[220:223], v[82:85]
	v_mfma_f32_16x16x32_bf16 v[72:75], v[180:183], v[228:231], v[72:75]
	v_mfma_f32_16x16x32_bf16 v[64:67], v[188:191], v[228:231], v[64:67]
	s_barrier
	s_add_i32 s67, s67, s39
	v_lshl_add_u64 v[200:201], s[46:47], 0, v[134:135]
	s_mov_b32 m0, s67
	ds_read_b128 v[192:195], v144 offset:16384
	ds_read_b128 v[196:199], v144 offset:17408
	ds_read_b128 v[208:211], v144 offset:18432
	ds_read_b128 v[212:215], v144 offset:19456
	ds_read_b128 v[216:219], v144 offset:20480
	ds_read_b128 v[220:223], v144 offset:21504
	ds_read_b128 v[224:227], v144 offset:22528
	ds_read_b128 v[228:231], v144 offset:23552
	global_load_lds_dwordx4 v[200:201], off
	s_add_i32 m0, s67, 0x2000
	s_add_u32 s68, s46, 0x40000
	v_lshl_add_u64 v[232:233], s[46:47], 0, v[130:131]
	s_addc_u32 s69, s47, 0
	s_add_i32 s67, s70, s39
	global_load_lds_dwordx4 v[232:233], off
	v_lshl_add_u64 v[234:235], s[68:69], 0, v[134:135]
	s_mov_b32 m0, s67
	v_lshl_add_u64 v[236:237], s[48:49], 0, v[132:133]
	global_load_lds_dwordx4 v[234:235], off
	v_lshl_add_u64 v[234:235], s[68:69], 0, v[130:131]
	s_add_i32 m0, s67, 0x2000
	s_nop 0
	global_load_lds_dwordx4 v[234:235], off
	v_lshl_add_u64 v[234:235], s[48:49], 0, v[136:137]
	s_mov_b32 m0, s50
	s_nop 0
	global_load_lds_dwordx4 v[234:235], off
	s_mov_b32 m0, s51
	s_nop 0
	global_load_lds_dwordx4 v[236:237], off
	s_waitcnt vmcnt(8)
	s_waitcnt lgkmcnt(0)
	s_barrier
	v_mfma_f32_16x16x32_bf16 v[60:63], v[146:149], v[192:195], v[60:63]
	v_mfma_f32_16x16x32_bf16 v[52:55], v[154:157], v[192:195], v[52:55]
	v_mfma_f32_16x16x32_bf16 v[44:47], v[146:149], v[208:211], v[44:47]
	v_mfma_f32_16x16x32_bf16 v[36:39], v[154:157], v[208:211], v[36:39]
	v_mfma_f32_16x16x32_bf16 v[28:31], v[146:149], v[216:219], v[28:31]
	v_mfma_f32_16x16x32_bf16 v[20:23], v[154:157], v[216:219], v[20:23]
	v_mfma_f32_16x16x32_bf16 v[12:15], v[146:149], v[224:227], v[12:15]
	v_mfma_f32_16x16x32_bf16 v[4:7], v[154:157], v[224:227], v[4:7]
	v_mfma_f32_16x16x32_bf16 v[60:63], v[150:153], v[196:199], v[60:63]
	v_mfma_f32_16x16x32_bf16 v[52:55], v[158:161], v[196:199], v[52:55]
	v_mfma_f32_16x16x32_bf16 v[44:47], v[150:153], v[212:215], v[44:47]
	v_mfma_f32_16x16x32_bf16 v[36:39], v[158:161], v[212:215], v[36:39]
	v_mfma_f32_16x16x32_bf16 v[28:31], v[150:153], v[220:223], v[28:31]
	v_mfma_f32_16x16x32_bf16 v[20:23], v[158:161], v[220:223], v[20:23]
	v_mfma_f32_16x16x32_bf16 v[12:15], v[150:153], v[228:231], v[12:15]
	v_mfma_f32_16x16x32_bf16 v[4:7], v[158:161], v[228:231], v[4:7]
	v_mfma_f32_16x16x32_bf16 v[56:59], v[176:179], v[192:195], v[56:59]
	v_mfma_f32_16x16x32_bf16 v[48:51], v[184:187], v[192:195], v[48:51]
	v_mfma_f32_16x16x32_bf16 v[40:43], v[176:179], v[208:211], v[40:43]
	v_mfma_f32_16x16x32_bf16 v[32:35], v[184:187], v[208:211], v[32:35]
	v_mfma_f32_16x16x32_bf16 v[24:27], v[176:179], v[216:219], v[24:27]
	v_mfma_f32_16x16x32_bf16 v[16:19], v[184:187], v[216:219], v[16:19]
	v_mfma_f32_16x16x32_bf16 v[8:11], v[176:179], v[224:227], v[8:11]
	v_mfma_f32_16x16x32_bf16 v[0:3], v[184:187], v[224:227], v[0:3]
	v_mfma_f32_16x16x32_bf16 v[56:59], v[180:183], v[196:199], v[56:59]
	v_mfma_f32_16x16x32_bf16 v[48:51], v[188:191], v[196:199], v[48:51]
	v_mfma_f32_16x16x32_bf16 v[40:43], v[180:183], v[212:215], v[40:43]
	v_mfma_f32_16x16x32_bf16 v[32:35], v[188:191], v[212:215], v[32:35]
	v_mfma_f32_16x16x32_bf16 v[24:27], v[180:183], v[220:223], v[24:27]
	v_mfma_f32_16x16x32_bf16 v[16:19], v[188:191], v[220:223], v[16:19]
	v_mfma_f32_16x16x32_bf16 v[8:11], v[180:183], v[228:231], v[8:11]
	v_mfma_f32_16x16x32_bf16 v[0:3], v[188:191], v[228:231], v[0:3]
	s_barrier
; #define PG8_STAGE(bufoff, gbase, voff) do { _Pragma("unroll") for (int _i = 0; _i < 2; ++_i) \
;         __builtin_amdgcn_global_load_lds((const unsigned*)((const char*)(gbase) + (voff)[_i]), (PG8_LAS unsigned*)(lds + (bufoff) + ldsw + _i * 8192), 16, 0, 0); } while (0)
; #define PG8_LDA(dst, b, h) do { _Pragma("unroll") for (int m = 0; m < 4; ++m) _Pragma("unroll") for (int k = 0; k < 2; ++k) dst[m][k] = *(const PG8_LAS bf16x8*)(lds + PG8_SA(b, h) + aoff + m * 2048 + k * 1024); } while (0)
; #define PG8_LDB(dst, b, h) do { _Pragma("unroll") for (int n = 0; n < 2; ++n) _Pragma("unroll") for (int k = 0; k < 2; ++k) dst[n][k] = *(const PG8_LAS bf16x8*)(lds + PG8_SB(b, h) + boff + n * 2048 + k * 1024); } while (0)
; #define PG8_MMA(ai, bj, At, Bt) do { __builtin_amdgcn_s_setprio(1); _Pragma("unroll") for (int m = 0; m < 4; ++m) _Pragma("unroll") for (int n = 0; n < 2; ++n) _Pragma("unroll") for (int k = 0; k < 2; ++k) \
;         acc[ai][bj][m][n] = __builtin_amdgcn_mfma_f32_16x16x32_bf16(Bt[n][k], At[m][k], acc[ai][bj][m][n], 0, 0, 0); __builtin_amdgcn_s_setprio(0); } while (0)
; #define PG8_WAIT_V(n) asm volatile("s_waitcnt vmcnt(" #n ")" ::: "memory")
; #define PG8_WAIT_L(n) asm volatile("s_waitcnt lgkmcnt(" #n ")" ::: "memory")
; #define PG8_BAR __builtin_amdgcn_s_barrier()
; #define PG8_SCHED __builtin_amdgcn_sched_barrier(0)
; template <class Epi, class Sched, bool ALIGN_EPI = false, bool SP2 = false>
; __device__ __forceinline__ void gemm_phase(PG8_LAS unsigned char* lds, const Gemm g, const Sched& S, const Epi& E) {
;     ...
;             PG8_LDB(B0, 1, 0); PG8_LDB(B1, 1, 1); PG8_SCHED; PG8_LDA(At, 1, 0); PG8_STAGE(PG8_SA(0, 1), a2 + hstep, voffA);
;             PG8_WAIT_V(8); PG8_WAIT_L(0); PG8_BAR; PG8_MMA(0, 0, At, B0); PG8_MMA(0, 1, At, B1); PG8_BAR; PG8_SCHED;
	s_add_i32 s67, 0, 0x18000
	v_add_u32_e32 v145, s67, v143
	s_add_i32 s68, 0, 0x1c000
	ds_read_b128 v[146:149], v145
	ds_read_b128 v[150:153], v145 offset:1024
	ds_read_b128 v[154:157], v145 offset:2048
	ds_read_b128 v[158:161], v145 offset:3072
	v_add_u32_e32 v145, s68, v143
	ds_read_b128 v[176:179], v145
	ds_read_b128 v[180:183], v145 offset:1024
	ds_read_b128 v[184:187], v145 offset:2048
	ds_read_b128 v[188:191], v145 offset:3072
	s_add_u32 s48, s48, 0x40000
	s_addc_u32 s49, s49, 0
	s_mov_b32 m0, s52
	v_lshl_add_u64 v[238:239], s[48:49], 0, v[136:137]
	ds_read_b128 v[192:195], v144 offset:32768
	ds_read_b128 v[196:199], v144 offset:33792
	ds_read_b128 v[208:211], v144 offset:34816
	ds_read_b128 v[212:215], v144 offset:35840
	ds_read_b128 v[216:219], v144 offset:36864
	ds_read_b128 v[220:223], v144 offset:37888
	ds_read_b128 v[224:227], v144 offset:38912
	ds_read_b128 v[228:231], v144 offset:39936
	global_load_lds_dwordx4 v[238:239], off
	v_lshl_add_u64 v[238:239], s[48:49], 0, v[132:133]
	s_mov_b32 m0, s53
	s_nop 0
	global_load_lds_dwordx4 v[238:239], off
	s_waitcnt vmcnt(8)
	s_waitcnt lgkmcnt(0)
	s_barrier
	v_mfma_f32_16x16x32_bf16 v[126:129], v[146:149], v[192:195], v[126:129]
	v_mfma_f32_16x16x32_bf16 v[118:121], v[154:157], v[192:195], v[118:121]
	v_mfma_f32_16x16x32_bf16 v[110:113], v[146:149], v[208:211], v[110:113]
	v_mfma_f32_16x16x32_bf16 v[102:105], v[154:157], v[208:211], v[102:105]
	v_mfma_f32_16x16x32_bf16 v[94:97], v[146:149], v[216:219], v[94:97]
	v_mfma_f32_16x16x32_bf16 v[86:89], v[154:157], v[216:219], v[86:89]
	v_mfma_f32_16x16x32_bf16 v[76:79], v[146:149], v[224:227], v[76:79]
	v_mfma_f32_16x16x32_bf16 v[68:71], v[154:157], v[224:227], v[68:71]
	v_mfma_f32_16x16x32_bf16 v[126:129], v[150:153], v[196:199], v[126:129]
	v_mfma_f32_16x16x32_bf16 v[118:121], v[158:161], v[196:199], v[118:121]
	v_mfma_f32_16x16x32_bf16 v[110:113], v[150:153], v[212:215], v[110:113]
	v_mfma_f32_16x16x32_bf16 v[102:105], v[158:161], v[212:215], v[102:105]
	v_mfma_f32_16x16x32_bf16 v[94:97], v[150:153], v[220:223], v[94:97]
	v_mfma_f32_16x16x32_bf16 v[86:89], v[158:161], v[220:223], v[86:89]
	v_mfma_f32_16x16x32_bf16 v[76:79], v[150:153], v[228:231], v[76:79]
	v_mfma_f32_16x16x32_bf16 v[68:71], v[158:161], v[228:231], v[68:71]
	v_mfma_f32_16x16x32_bf16 v[122:125], v[176:179], v[192:195], v[122:125]
	v_mfma_f32_16x16x32_bf16 v[114:117], v[184:187], v[192:195], v[114:117]
	v_mfma_f32_16x16x32_bf16 v[106:109], v[176:179], v[208:211], v[106:109]
	v_mfma_f32_16x16x32_bf16 v[98:101], v[184:187], v[208:211], v[98:101]
	v_mfma_f32_16x16x32_bf16 v[90:93], v[176:179], v[216:219], v[90:93]
	v_mfma_f32_16x16x32_bf16 v[82:85], v[184:187], v[216:219], v[82:85]
	v_mfma_f32_16x16x32_bf16 v[72:75], v[176:179], v[224:227], v[72:75]
	v_mfma_f32_16x16x32_bf16 v[64:67], v[184:187], v[224:227], v[64:67]
	v_mfma_f32_16x16x32_bf16 v[122:125], v[180:183], v[196:199], v[122:125]
	v_mfma_f32_16x16x32_bf16 v[114:117], v[188:191], v[196:199], v[114:117]
	v_mfma_f32_16x16x32_bf16 v[106:109], v[180:183], v[212:215], v[106:109]
	v_mfma_f32_16x16x32_bf16 v[98:101], v[188:191], v[212:215], v[98:101]
	v_mfma_f32_16x16x32_bf16 v[90:93], v[180:183], v[220:223], v[90:93]
	v_mfma_f32_16x16x32_bf16 v[82:85], v[188:191], v[220:223], v[82:85]
	v_mfma_f32_16x16x32_bf16 v[72:75], v[180:183], v[228:231], v[72:75]
	v_mfma_f32_16x16x32_bf16 v[64:67], v[188:191], v[228:231], v[64:67]
	s_barrier
; #define PG8_STAGE(bufoff, gbase, voff) do { _Pragma("unroll") for (int _i = 0; _i < 2; ++_i) \
;         __builtin_amdgcn_global_load_lds((const unsigned*)((const char*)(gbase) + (voff)[_i]), (PG8_LAS unsigned*)(lds + (bufoff) + ldsw + _i * 8192), 16, 0, 0); } while (0)
; #define PG8_LDA(dst, b, h) do { _Pragma("unroll") for (int m = 0; m < 4; ++m) _Pragma("unroll") for (int k = 0; k < 2; ++k) dst[m][k] = *(const PG8_LAS bf16x8*)(lds + PG8_SA(b, h) + aoff + m * 2048 + k * 1024); } while (0)
; #define PG8_MMA(ai, bj, At, Bt) do { __builtin_amdgcn_s_setprio(1); _Pragma("unroll") for (int m = 0; m < 4; ++m) _Pragma("unroll") for (int n = 0; n < 2; ++n) _Pragma("unroll") for (int k = 0; k < 2; ++k) \
;         acc[ai][bj][m][n] = __builtin_amdgcn_mfma_f32_16x16x32_bf16(Bt[n][k], At[m][k], acc[ai][bj][m][n], 0, 0, 0); __builtin_amdgcn_s_setprio(0); } while (0)
; #define PG8_WAIT_V(n) asm volatile("s_waitcnt vmcnt(" #n ")" ::: "memory")
; #define PG8_WAIT_L(n) asm volatile("s_waitcnt lgkmcnt(" #n ")" ::: "memory")
; #define PG8_BAR __builtin_amdgcn_s_barrier()
; #define PG8_SCHED __builtin_amdgcn_sched_barrier(0)
; template <class Epi, class Sched, bool ALIGN_EPI = false, bool SP2 = false>
; __device__ __forceinline__ void gemm_phase(PG8_LAS unsigned char* lds, const Gemm g, const Sched& S, const Epi& E) {
;     ...
;             PG8_LDA(At, 1, 1); PG8_STAGE(PG8_SB(1, 0), b3, voffB); PG8_STAGE(PG8_SB(1, 1), b3 + hstep, voffB); PG8_STAGE(PG8_SA(1, 0), a3, voffA);
;             PG8_WAIT_V(8); PG8_WAIT_L(0); PG8_BAR; PG8_MMA(1, 0, At, B0); PG8_MMA(1, 1, At, B1); PG8_BAR; PG8_SCHED;
;     ...
;         }
;         if constexpr (ALIGN_EPI) { if (wr == 0) PG8_BAR; }
	s_add_i32 s48, s67, s39
	v_lshl_add_u64 v[200:201], v[200:201], 0, s[40:41]
	s_mov_b32 m0, s48
	ds_read_b128 v[192:195], v144 offset:49152
	ds_read_b128 v[196:199], v144 offset:50176
	ds_read_b128 v[208:211], v144 offset:51200
	ds_read_b128 v[212:215], v144 offset:52224
	ds_read_b128 v[216:219], v144 offset:53248
	ds_read_b128 v[220:223], v144 offset:54272
	ds_read_b128 v[224:227], v144 offset:55296
	ds_read_b128 v[228:231], v144 offset:56320
	global_load_lds_dwordx4 v[200:201], off
	s_add_i32 m0, s48, 0x2000
	s_add_u32 s46, s46, 0x40080
	v_lshl_add_u64 v[200:201], v[232:233], 0, s[40:41]
	s_addc_u32 s47, s47, 0
	s_add_i32 s48, s68, s39
	global_load_lds_dwordx4 v[200:201], off
	v_lshl_add_u64 v[200:201], s[46:47], 0, v[134:135]
	s_mov_b32 m0, s48
	s_nop 0
	global_load_lds_dwordx4 v[200:201], off
	v_lshl_add_u64 v[200:201], s[46:47], 0, v[130:131]
	s_add_i32 m0, s48, 0x2000
	s_nop 0
	global_load_lds_dwordx4 v[200:201], off
	v_lshl_add_u64 v[200:201], v[234:235], 0, s[40:41]
	s_mov_b32 m0, s56
	s_nop 0
	global_load_lds_dwordx4 v[200:201], off
	v_lshl_add_u64 v[200:201], v[236:237], 0, s[40:41]
	s_mov_b32 m0, s57
	s_nop 0
	global_load_lds_dwordx4 v[200:201], off
	s_waitcnt vmcnt(8)
	s_waitcnt lgkmcnt(0)
	s_barrier
	v_mfma_f32_16x16x32_bf16 v[60:63], v[146:149], v[192:195], v[60:63]
	v_mfma_f32_16x16x32_bf16 v[52:55], v[154:157], v[192:195], v[52:55]
	v_mfma_f32_16x16x32_bf16 v[44:47], v[146:149], v[208:211], v[44:47]
	v_mfma_f32_16x16x32_bf16 v[36:39], v[154:157], v[208:211], v[36:39]
	v_mfma_f32_16x16x32_bf16 v[28:31], v[146:149], v[216:219], v[28:31]
	v_mfma_f32_16x16x32_bf16 v[20:23], v[154:157], v[216:219], v[20:23]
	v_mfma_f32_16x16x32_bf16 v[12:15], v[146:149], v[224:227], v[12:15]
	v_mfma_f32_16x16x32_bf16 v[4:7], v[154:157], v[224:227], v[4:7]
	v_mfma_f32_16x16x32_bf16 v[60:63], v[150:153], v[196:199], v[60:63]
	v_mfma_f32_16x16x32_bf16 v[52:55], v[158:161], v[196:199], v[52:55]
	v_mfma_f32_16x16x32_bf16 v[44:47], v[150:153], v[212:215], v[44:47]
	v_mfma_f32_16x16x32_bf16 v[36:39], v[158:161], v[212:215], v[36:39]
	v_mfma_f32_16x16x32_bf16 v[28:31], v[150:153], v[220:223], v[28:31]
	v_mfma_f32_16x16x32_bf16 v[20:23], v[158:161], v[220:223], v[20:23]
	v_mfma_f32_16x16x32_bf16 v[12:15], v[150:153], v[228:231], v[12:15]
	v_mfma_f32_16x16x32_bf16 v[4:7], v[158:161], v[228:231], v[4:7]
	v_mfma_f32_16x16x32_bf16 v[56:59], v[176:179], v[192:195], v[56:59]
	v_mfma_f32_16x16x32_bf16 v[48:51], v[184:187], v[192:195], v[48:51]
	v_mfma_f32_16x16x32_bf16 v[40:43], v[176:179], v[208:211], v[40:43]
	v_mfma_f32_16x16x32_bf16 v[32:35], v[184:187], v[208:211], v[32:35]
	v_mfma_f32_16x16x32_bf16 v[24:27], v[176:179], v[216:219], v[24:27]
	v_mfma_f32_16x16x32_bf16 v[16:19], v[184:187], v[216:219], v[16:19]
	v_mfma_f32_16x16x32_bf16 v[8:11], v[176:179], v[224:227], v[8:11]
	v_mfma_f32_16x16x32_bf16 v[0:3], v[184:187], v[224:227], v[0:3]
	v_mfma_f32_16x16x32_bf16 v[56:59], v[180:183], v[196:199], v[56:59]
	v_mfma_f32_16x16x32_bf16 v[48:51], v[188:191], v[196:199], v[48:51]
	v_mfma_f32_16x16x32_bf16 v[40:43], v[180:183], v[212:215], v[40:43]
	v_mfma_f32_16x16x32_bf16 v[32:35], v[188:191], v[212:215], v[32:35]
	v_mfma_f32_16x16x32_bf16 v[24:27], v[180:183], v[220:223], v[24:27]
	v_mfma_f32_16x16x32_bf16 v[16:19], v[188:191], v[220:223], v[16:19]
	v_mfma_f32_16x16x32_bf16 v[8:11], v[180:183], v[228:231], v[8:11]
	v_mfma_f32_16x16x32_bf16 v[0:3], v[188:191], v[228:231], v[0:3]
	s_barrier
	s_add_i32 s66, s66, 2
	s_add_u32 s44, s44, 0x100
	s_addc_u32 s45, s45, 0
	s_add_u32 s64, s64, 0x100
	s_addc_u32 s65, s65, 0
	s_cmp_gt_u32 s66, 13
	s_cbranch_scc0 .LBB0_110
	s_setprio 0
	s_and_b64 vcc, exec, s[12:13]
	s_cbranch_vccz .LBB0_113
	s_barrier

; #define PG8_STAGE(bufoff, gbase, voff) do { _Pragma("unroll") for (int _i = 0; _i < 2; ++_i) \
;         __builtin_amdgcn_global_load_lds((const unsigned*)((const char*)(gbase) + (voff)[_i]), (PG8_LAS unsigned*)(lds + (bufoff) + ldsw + _i * 8192), 16, 0, 0); } while (0)
; #define PG8_LDA(dst, b, h) do { _Pragma("unroll") for (int m = 0; m < 4; ++m) _Pragma("unroll") for (int k = 0; k < 2; ++k) dst[m][k] = *(const PG8_LAS bf16x8*)(lds + PG8_SA(b, h) + aoff + m * 2048 + k * 1024); } while (0)
; #define PG8_LDB(dst, b, h) do { _Pragma("unroll") for (int n = 0; n < 2; ++n) _Pragma("unroll") for (int k = 0; k < 2; ++k) dst[n][k] = *(const PG8_LAS bf16x8*)(lds + PG8_SB(b, h) + boff + n * 2048 + k * 1024); } while (0)
; #define PG8_WAIT_V(n) asm volatile("s_waitcnt vmcnt(" #n ")" ::: "memory")
; template <class Epi, class Sched, bool ALIGN_EPI = false, bool SP2 = false>
; __device__ __forceinline__ void gemm_phase(PG8_LAS unsigned char* lds, const Gemm g, const Sched& S, const Epi& E) {
;     ...
;         const char* nA = has_next ? (const char*)(nxt.sw ? g.A2 : g.A) + (size_t)nxt.pm * tstep : cA; const char* nB = has_next ? (const char*)(nxt.sw ? g.Bt2 : g.Bt) + (size_t)nxt.pn * tstep : cB;
;         for (int t = 0; t < nt; t += 2) {
;             if constexpr (Epi::PF_TRIPS > 0) { if (t == nt - 2 * Epi::PF_TRIPS) E.prefetch(cur, tid, lds + STAGE_BYTES + wid * 512); }
;             const bool last = (t == nt - 2);
;             const char* a1 = cA + (size_t)(t + 1) * kstep;
;             const char* a2 = last ? nA : cA + (size_t)(t + 2) * kstep; const char* b2 = last ? nB : cB + (size_t)(t + 2) * kstep;
;             const char* a3 = a2 + kstep; const char* b3 = b2 + kstep;
;             if (last && has_next) S.a_ready(nxt);
;             if constexpr (SP2) {
;             PG8_LDB(B0, 0, 0); PG8_LDB(B1, 0, 1); PG8_SCHED; PG8_LDA(At, 0, 0); PG8_STAGE(PG8_SA(1, 1), a1 + hstep, voffA);
;             PG8_WAIT_V(8); PG8_WAIT_L(0); PG8_BAR; PG8_MMA(0, 0, At, B0); PG8_MMA(0, 1, At, B1); PG8_BAR; PG8_SCHED;
;     ...
; #pragma unroll
;         for (int a = 0; a < 2; ++a)
; #pragma unroll
;             for (int b = 0; b < 2; ++b)
; #pragma unroll
;                 for (int m = 0; m < 4; ++m)
; #pragma unroll
;                     for (int n = 0; n < 2; ++n) acc[a][b][m][n] = (f32x4){0.f, 0.f, 0.f, 0.f};
;         cur = nxt; cA = nA; cB = nB; ++ui;
.LBB0_128:
	s_ashr_i32 s19, s18, 31
	s_lshl_b64 s[42:43], s[18:19], 19
	s_add_u32 s42, s30, s42
	s_addc_u32 s43, s31, s43
	s_and_b64 s[44:45], s[4:5], exec
	s_cselect_b32 s19, s43, s47
	s_cselect_b32 s64, s42, s46
	s_ashr_i32 s17, s16, 31
	s_lshl_b64 s[44:45], s[16:17], 19
	s_add_u32 s44, s38, s44
	s_addc_u32 s45, s39, s45
	s_and_b64 s[50:51], s[4:5], exec
	s_cselect_b32 s17, s45, s49
	s_cselect_b32 s65, s44, s48
	s_add_u32 s46, s46, 0x40080
	s_addc_u32 s47, s47, 0
	s_add_u32 s66, s48, 0x100
	v_mov_b32_e32 v0, 0
	s_addc_u32 s67, s49, 0
	s_mov_b32 s68, -2
	v_mov_b32_e32 v1, v0
	v_mov_b32_e32 v2, v0
	v_mov_b32_e32 v3, v0
	v_mov_b32_e32 v4, v0
	v_mov_b32_e32 v5, v0
	v_mov_b32_e32 v6, v0
	v_mov_b32_e32 v7, v0
	v_mov_b32_e32 v12, v0
	v_mov_b32_e32 v13, v0
	v_mov_b32_e32 v14, v0
	v_mov_b32_e32 v15, v0
	v_mov_b32_e32 v20, v0
	v_mov_b32_e32 v21, v0
	v_mov_b32_e32 v22, v0
	v_mov_b32_e32 v23, v0
	v_mov_b32_e32 v28, v0
	v_mov_b32_e32 v29, v0
	v_mov_b32_e32 v30, v0
	v_mov_b32_e32 v31, v0
	v_mov_b32_e32 v36, v0
	v_mov_b32_e32 v37, v0
	v_mov_b32_e32 v38, v0
	v_mov_b32_e32 v39, v0
	v_mov_b32_e32 v44, v0
	v_mov_b32_e32 v45, v0
	v_mov_b32_e32 v46, v0
	v_mov_b32_e32 v47, v0
	v_mov_b32_e32 v52, v0
	v_mov_b32_e32 v53, v0
	v_mov_b32_e32 v54, v0
	v_mov_b32_e32 v55, v0
	v_mov_b32_e32 v8, v0
	v_mov_b32_e32 v9, v0
	v_mov_b32_e32 v10, v0
	v_mov_b32_e32 v11, v0
	v_mov_b32_e32 v16, v0
	v_mov_b32_e32 v17, v0
	v_mov_b32_e32 v18, v0
	v_mov_b32_e32 v19, v0
	v_mov_b32_e32 v24, v0
	v_mov_b32_e32 v25, v0
	v_mov_b32_e32 v26, v0
	v_mov_b32_e32 v27, v0
	v_mov_b32_e32 v32, v0
	v_mov_b32_e32 v33, v0
	v_mov_b32_e32 v34, v0
	v_mov_b32_e32 v35, v0
	v_mov_b32_e32 v40, v0
	v_mov_b32_e32 v41, v0
	v_mov_b32_e32 v42, v0
	v_mov_b32_e32 v43, v0
	v_mov_b32_e32 v48, v0
	v_mov_b32_e32 v49, v0
	v_mov_b32_e32 v50, v0
	v_mov_b32_e32 v51, v0
	v_mov_b32_e32 v56, v0
	v_mov_b32_e32 v57, v0
	v_mov_b32_e32 v58, v0
	v_mov_b32_e32 v59, v0
	v_mov_b32_e32 v60, v0
	v_mov_b32_e32 v61, v0
	v_mov_b32_e32 v62, v0
	v_mov_b32_e32 v63, v0
	v_mov_b32_e32 v64, v0
	v_mov_b32_e32 v65, v0
	v_mov_b32_e32 v66, v0
	v_mov_b32_e32 v67, v0
	v_mov_b32_e32 v68, v0
	v_mov_b32_e32 v69, v0
	v_mov_b32_e32 v70, v0
	v_mov_b32_e32 v71, v0
	v_mov_b32_e32 v76, v0
	v_mov_b32_e32 v77, v0
	v_mov_b32_e32 v78, v0
	v_mov_b32_e32 v79, v0
	v_mov_b32_e32 v86, v0
	v_mov_b32_e32 v87, v0
	v_mov_b32_e32 v88, v0
	v_mov_b32_e32 v89, v0
	v_mov_b32_e32 v94, v0
	v_mov_b32_e32 v95, v0
	v_mov_b32_e32 v96, v0
	v_mov_b32_e32 v97, v0
	v_mov_b32_e32 v102, v0
	v_mov_b32_e32 v103, v0
	v_mov_b32_e32 v104, v0
	v_mov_b32_e32 v105, v0
	v_mov_b32_e32 v110, v0
	v_mov_b32_e32 v111, v0
	v_mov_b32_e32 v112, v0
	v_mov_b32_e32 v113, v0
	v_mov_b32_e32 v118, v0
	v_mov_b32_e32 v119, v0
	v_mov_b32_e32 v120, v0
	v_mov_b32_e32 v121, v0
	v_mov_b32_e32 v72, v0
	v_mov_b32_e32 v73, v0
	v_mov_b32_e32 v74, v0
	v_mov_b32_e32 v75, v0
	v_mov_b32_e32 v82, v0
	v_mov_b32_e32 v83, v0
	v_mov_b32_e32 v84, v0
	v_mov_b32_e32 v85, v0
	v_mov_b32_e32 v90, v0
	v_mov_b32_e32 v91, v0
	v_mov_b32_e32 v92, v0
	v_mov_b32_e32 v93, v0
	v_mov_b32_e32 v98, v0
	v_mov_b32_e32 v99, v0
	v_mov_b32_e32 v100, v0
	v_mov_b32_e32 v101, v0
	v_mov_b32_e32 v106, v0
	v_mov_b32_e32 v107, v0
	v_mov_b32_e32 v108, v0
	v_mov_b32_e32 v109, v0
	v_mov_b32_e32 v114, v0
	v_mov_b32_e32 v115, v0
	v_mov_b32_e32 v116, v0
	v_mov_b32_e32 v117, v0
	v_mov_b32_e32 v122, v0
	v_mov_b32_e32 v123, v0
	v_mov_b32_e32 v124, v0
	v_mov_b32_e32 v125, v0
	v_mov_b32_e32 v126, v0
	v_mov_b32_e32 v127, v0
	v_mov_b32_e32 v128, v0
	v_mov_b32_e32 v129, v0
	v_readfirstlane_b32 s100, v202
	s_nop 3
	s_lshr_b32 s100, s100, 8
	s_cmp_eq_u32 s100, 0
	s_cbranch_scc1 .Lsp_cin
	s_setprio 1
.Lsp_cin:
.LBB0_129:
	s_add_u32 s48, s46, 0xfffc0080
	s_addc_u32 s49, s47, -1
	s_add_i32 s69, 0, 0x10000
	s_cmp_eq_u32 s68, 12
	s_cselect_b32 s51, s19, s49
	s_cselect_b32 s50, s64, s48
	v_add_u32_e32 v142, s69, v148
	s_cselect_b32 s49, s17, s67
	s_cselect_b32 s48, s65, s66
	s_add_i32 s72, 0, 0x14000
	ds_read_b128 v[150:153], v142
	ds_read_b128 v[154:157], v142 offset:1024
	ds_read_b128 v[158:161], v142 offset:2048
	ds_read_b128 v[176:179], v142 offset:3072
	v_add_u32_e32 v142, s72, v148
	ds_read_b128 v[180:183], v142
	ds_read_b128 v[184:187], v142 offset:1024
	ds_read_b128 v[188:191], v142 offset:2048
	ds_read_b128 v[192:195], v142 offset:3072
	v_lshl_add_u64 v[142:143], s[46:47], 0, v[138:139]
	s_add_i32 m0, s53, 0xc000
	ds_read_b128 v[196:199], v149
	ds_read_b128 v[208:211], v149 offset:1024
	ds_read_b128 v[212:215], v149 offset:2048
	ds_read_b128 v[216:219], v149 offset:3072
	ds_read_b128 v[220:223], v149 offset:4096
	ds_read_b128 v[224:227], v149 offset:5120
	ds_read_b128 v[228:231], v149 offset:6144
	ds_read_b128 v[232:235], v149 offset:7168
	global_load_lds_dwordx4 v[142:143], off
	v_lshl_add_u64 v[142:143], s[46:47], 0, v[140:141]
	s_add_i32 m0, s53, 0xe000
	s_nop 0
	global_load_lds_dwordx4 v[142:143], off
	s_waitcnt vmcnt(8)
	s_waitcnt lgkmcnt(0)
	s_barrier
; #define PG8_STAGE(bufoff, gbase, voff) do { _Pragma("unroll") for (int _i = 0; _i < 2; ++_i) \
;         __builtin_amdgcn_global_load_lds((const unsigned*)((const char*)(gbase) + (voff)[_i]), (PG8_LAS unsigned*)(lds + (bufoff) + ldsw + _i * 8192), 16, 0, 0); } while (0)
; #define PG8_LDA(dst, b, h) do { _Pragma("unroll") for (int m = 0; m < 4; ++m) _Pragma("unroll") for (int k = 0; k < 2; ++k) dst[m][k] = *(const PG8_LAS bf16x8*)(lds + PG8_SA(b, h) + aoff + m * 2048 + k * 1024); } while (0)
; #define PG8_MMA(ai, bj, At, Bt) do { __builtin_amdgcn_s_setprio(1); _Pragma("unroll") for (int m = 0; m < 4; ++m) _Pragma("unroll") for (int n = 0; n < 2; ++n) _Pragma("unroll") for (int k = 0; k < 2; ++k) \
;         acc[ai][bj][m][n] = __builtin_amdgcn_mfma_f32_16x16x32_bf16(Bt[n][k], At[m][k], acc[ai][bj][m][n], 0, 0, 0); __builtin_amdgcn_s_setprio(0); } while (0)
; #define PG8_WAIT_V(n) asm volatile("s_waitcnt vmcnt(" #n ")" ::: "memory")
; #define PG8_WAIT_L(n) asm volatile("s_waitcnt lgkmcnt(" #n ")" ::: "memory")
; #define PG8_BAR __builtin_amdgcn_s_barrier()
; #define PG8_SCHED __builtin_amdgcn_sched_barrier(0)
; template <class Epi, class Sched, bool ALIGN_EPI = false, bool SP2 = false>
; __device__ __forceinline__ void gemm_phase(PG8_LAS unsigned char* lds, const Gemm g, const Sched& S, const Epi& E) {
;     ...
;             PG8_WAIT_V(8); PG8_WAIT_L(0); PG8_BAR; PG8_MMA(0, 0, At, B0); PG8_MMA(0, 1, At, B1); PG8_BAR; PG8_SCHED;
;             PG8_LDA(At, 0, 1); PG8_STAGE(PG8_SB(0, 0), b2, voffB); PG8_STAGE(PG8_SB(0, 1), b2 + hstep, voffB); PG8_STAGE(PG8_SA(0, 0), a2, voffA);
;             PG8_WAIT_V(8); PG8_WAIT_L(0); PG8_BAR; PG8_MMA(1, 0, At, B0); PG8_MMA(1, 1, At, B1); PG8_BAR; PG8_SCHED;
	v_mfma_f32_16x16x32_bf16 v[126:129], v[150:153], v[196:199], v[126:129]
	v_mfma_f32_16x16x32_bf16 v[122:125], v[158:161], v[196:199], v[122:125]
	v_mfma_f32_16x16x32_bf16 v[114:117], v[150:153], v[212:215], v[114:117]
	v_mfma_f32_16x16x32_bf16 v[106:109], v[158:161], v[212:215], v[106:109]
	v_mfma_f32_16x16x32_bf16 v[98:101], v[150:153], v[220:223], v[98:101]
	v_mfma_f32_16x16x32_bf16 v[90:93], v[158:161], v[220:223], v[90:93]
	v_mfma_f32_16x16x32_bf16 v[82:85], v[150:153], v[228:231], v[82:85]
	v_mfma_f32_16x16x32_bf16 v[72:75], v[158:161], v[228:231], v[72:75]
	v_mfma_f32_16x16x32_bf16 v[126:129], v[154:157], v[208:211], v[126:129]
	v_mfma_f32_16x16x32_bf16 v[122:125], v[176:179], v[208:211], v[122:125]
	v_mfma_f32_16x16x32_bf16 v[114:117], v[154:157], v[216:219], v[114:117]
	v_mfma_f32_16x16x32_bf16 v[106:109], v[176:179], v[216:219], v[106:109]
	v_mfma_f32_16x16x32_bf16 v[98:101], v[154:157], v[224:227], v[98:101]
	v_mfma_f32_16x16x32_bf16 v[90:93], v[176:179], v[224:227], v[90:93]
	v_mfma_f32_16x16x32_bf16 v[82:85], v[154:157], v[232:235], v[82:85]
	v_mfma_f32_16x16x32_bf16 v[72:75], v[176:179], v[232:235], v[72:75]
	v_mfma_f32_16x16x32_bf16 v[118:121], v[180:183], v[196:199], v[118:121]
	v_mfma_f32_16x16x32_bf16 v[110:113], v[188:191], v[196:199], v[110:113]
	v_mfma_f32_16x16x32_bf16 v[102:105], v[180:183], v[212:215], v[102:105]
	v_mfma_f32_16x16x32_bf16 v[94:97], v[188:191], v[212:215], v[94:97]
	v_mfma_f32_16x16x32_bf16 v[86:89], v[180:183], v[220:223], v[86:89]
	v_mfma_f32_16x16x32_bf16 v[76:79], v[188:191], v[220:223], v[76:79]
	v_mfma_f32_16x16x32_bf16 v[68:71], v[180:183], v[228:231], v[68:71]
	v_mfma_f32_16x16x32_bf16 v[64:67], v[188:191], v[228:231], v[64:67]
	v_mfma_f32_16x16x32_bf16 v[118:121], v[184:187], v[208:211], v[118:121]
	v_mfma_f32_16x16x32_bf16 v[110:113], v[192:195], v[208:211], v[110:113]
	v_mfma_f32_16x16x32_bf16 v[102:105], v[184:187], v[216:219], v[102:105]
	v_mfma_f32_16x16x32_bf16 v[94:97], v[192:195], v[216:219], v[94:97]
	v_mfma_f32_16x16x32_bf16 v[86:89], v[184:187], v[224:227], v[86:89]
	v_mfma_f32_16x16x32_bf16 v[76:79], v[192:195], v[224:227], v[76:79]
	v_mfma_f32_16x16x32_bf16 v[68:71], v[184:187], v[232:235], v[68:71]
	v_mfma_f32_16x16x32_bf16 v[64:67], v[192:195], v[232:235], v[64:67]
	s_barrier
	s_add_i32 s69, s69, s52
	v_lshl_add_u64 v[142:143], s[48:49], 0, v[134:135]
	s_mov_b32 m0, s69
	ds_read_b128 v[196:199], v149 offset:16384
	ds_read_b128 v[208:211], v149 offset:17408
	ds_read_b128 v[212:215], v149 offset:18432
	ds_read_b128 v[216:219], v149 offset:19456
	ds_read_b128 v[220:223], v149 offset:20480
	ds_read_b128 v[224:227], v149 offset:21504
	ds_read_b128 v[228:231], v149 offset:22528
	ds_read_b128 v[232:235], v149 offset:23552
	global_load_lds_dwordx4 v[142:143], off
	s_add_i32 m0, s69, 0x2000
	s_add_u32 s70, s48, 0x40000
	v_lshl_add_u64 v[146:147], s[48:49], 0, v[130:131]
	s_addc_u32 s71, s49, 0
	s_add_i32 s69, s72, s52
	global_load_lds_dwordx4 v[146:147], off
	v_lshl_add_u64 v[200:201], s[70:71], 0, v[134:135]
	s_mov_b32 m0, s69
	v_lshl_add_u64 v[236:237], s[50:51], 0, v[132:133]
	global_load_lds_dwordx4 v[200:201], off
	v_lshl_add_u64 v[200:201], s[70:71], 0, v[130:131]
	s_add_i32 m0, s69, 0x2000
	s_nop 0
	global_load_lds_dwordx4 v[200:201], off
	v_lshl_add_u64 v[200:201], s[50:51], 0, v[136:137]
	s_mov_b32 m0, s53
	s_nop 0
	global_load_lds_dwordx4 v[200:201], off
	s_mov_b32 m0, s54
	s_nop 0
	global_load_lds_dwordx4 v[236:237], off
	s_waitcnt vmcnt(8)
	s_waitcnt lgkmcnt(0)
	s_barrier
	v_mfma_f32_16x16x32_bf16 v[60:63], v[150:153], v[196:199], v[60:63]
	v_mfma_f32_16x16x32_bf16 v[56:59], v[158:161], v[196:199], v[56:59]
	v_mfma_f32_16x16x32_bf16 v[48:51], v[150:153], v[212:215], v[48:51]
	v_mfma_f32_16x16x32_bf16 v[40:43], v[158:161], v[212:215], v[40:43]
	v_mfma_f32_16x16x32_bf16 v[32:35], v[150:153], v[220:223], v[32:35]
	v_mfma_f32_16x16x32_bf16 v[24:27], v[158:161], v[220:223], v[24:27]
	v_mfma_f32_16x16x32_bf16 v[16:19], v[150:153], v[228:231], v[16:19]
	v_mfma_f32_16x16x32_bf16 v[8:11], v[158:161], v[228:231], v[8:11]
	v_mfma_f32_16x16x32_bf16 v[60:63], v[154:157], v[208:211], v[60:63]
	v_mfma_f32_16x16x32_bf16 v[56:59], v[176:179], v[208:211], v[56:59]
	v_mfma_f32_16x16x32_bf16 v[48:51], v[154:157], v[216:219], v[48:51]
	v_mfma_f32_16x16x32_bf16 v[40:43], v[176:179], v[216:219], v[40:43]
	v_mfma_f32_16x16x32_bf16 v[32:35], v[154:157], v[224:227], v[32:35]
	v_mfma_f32_16x16x32_bf16 v[24:27], v[176:179], v[224:227], v[24:27]
	v_mfma_f32_16x16x32_bf16 v[16:19], v[154:157], v[232:235], v[16:19]
	v_mfma_f32_16x16x32_bf16 v[8:11], v[176:179], v[232:235], v[8:11]
	v_mfma_f32_16x16x32_bf16 v[52:55], v[180:183], v[196:199], v[52:55]
	v_mfma_f32_16x16x32_bf16 v[44:47], v[188:191], v[196:199], v[44:47]
	v_mfma_f32_16x16x32_bf16 v[36:39], v[180:183], v[212:215], v[36:39]
	v_mfma_f32_16x16x32_bf16 v[28:31], v[188:191], v[212:215], v[28:31]
	v_mfma_f32_16x16x32_bf16 v[20:23], v[180:183], v[220:223], v[20:23]
	v_mfma_f32_16x16x32_bf16 v[12:15], v[188:191], v[220:223], v[12:15]
	v_mfma_f32_16x16x32_bf16 v[4:7], v[180:183], v[228:231], v[4:7]
	v_mfma_f32_16x16x32_bf16 v[0:3], v[188:191], v[228:231], v[0:3]
	v_mfma_f32_16x16x32_bf16 v[52:55], v[184:187], v[208:211], v[52:55]
	v_mfma_f32_16x16x32_bf16 v[44:47], v[192:195], v[208:211], v[44:47]
	v_mfma_f32_16x16x32_bf16 v[36:39], v[184:187], v[216:219], v[36:39]
	v_mfma_f32_16x16x32_bf16 v[28:31], v[192:195], v[216:219], v[28:31]
	v_mfma_f32_16x16x32_bf16 v[20:23], v[184:187], v[224:227], v[20:23]
	v_mfma_f32_16x16x32_bf16 v[12:15], v[192:195], v[224:227], v[12:15]
	v_mfma_f32_16x16x32_bf16 v[4:7], v[184:187], v[232:235], v[4:7]
	v_mfma_f32_16x16x32_bf16 v[0:3], v[192:195], v[232:235], v[0:3]
	s_barrier
; #define PG8_STAGE(bufoff, gbase, voff) do { _Pragma("unroll") for (int _i = 0; _i < 2; ++_i) \
;         __builtin_amdgcn_global_load_lds((const unsigned*)((const char*)(gbase) + (voff)[_i]), (PG8_LAS unsigned*)(lds + (bufoff) + ldsw + _i * 8192), 16, 0, 0); } while (0)
; #define PG8_LDA(dst, b, h) do { _Pragma("unroll") for (int m = 0; m < 4; ++m) _Pragma("unroll") for (int k = 0; k < 2; ++k) dst[m][k] = *(const PG8_LAS bf16x8*)(lds + PG8_SA(b, h) + aoff + m * 2048 + k * 1024); } while (0)
; #define PG8_LDB(dst, b, h) do { _Pragma("unroll") for (int n = 0; n < 2; ++n) _Pragma("unroll") for (int k = 0; k < 2; ++k) dst[n][k] = *(const PG8_LAS bf16x8*)(lds + PG8_SB(b, h) + boff + n * 2048 + k * 1024); } while (0)
; #define PG8_MMA(ai, bj, At, Bt) do { __builtin_amdgcn_s_setprio(1); _Pragma("unroll") for (int m = 0; m < 4; ++m) _Pragma("unroll") for (int n = 0; n < 2; ++n) _Pragma("unroll") for (int k = 0; k < 2; ++k) \
;         acc[ai][bj][m][n] = __builtin_amdgcn_mfma_f32_16x16x32_bf16(Bt[n][k], At[m][k], acc[ai][bj][m][n], 0, 0, 0); __builtin_amdgcn_s_setprio(0); } while (0)
; #define PG8_WAIT_V(n) asm volatile("s_waitcnt vmcnt(" #n ")" ::: "memory")
; #define PG8_WAIT_L(n) asm volatile("s_waitcnt lgkmcnt(" #n ")" ::: "memory")
; #define PG8_BAR __builtin_amdgcn_s_barrier()
; #define PG8_SCHED __builtin_amdgcn_sched_barrier(0)
; template <class Epi, class Sched, bool ALIGN_EPI = false, bool SP2 = false>
; __device__ __forceinline__ void gemm_phase(PG8_LAS unsigned char* lds, const Gemm g, const Sched& S, const Epi& E) {
;     ...
;             PG8_LDB(B0, 1, 0); PG8_LDB(B1, 1, 1); PG8_SCHED; PG8_LDA(At, 1, 0); PG8_STAGE(PG8_SA(0, 1), a2 + hstep, voffA);
;             PG8_WAIT_V(8); PG8_WAIT_L(0); PG8_BAR; PG8_MMA(0, 0, At, B0); PG8_MMA(0, 1, At, B1); PG8_BAR; PG8_SCHED;
	s_add_i32 s69, 0, 0x18000
	v_add_u32_e32 v144, s69, v148
	s_add_i32 s70, 0, 0x1c000
	ds_read_b128 v[150:153], v144
	ds_read_b128 v[154:157], v144 offset:1024
	ds_read_b128 v[158:161], v144 offset:2048
	ds_read_b128 v[176:179], v144 offset:3072
	v_add_u32_e32 v144, s70, v148
	ds_read_b128 v[180:183], v144
	ds_read_b128 v[184:187], v144 offset:1024
	ds_read_b128 v[188:191], v144 offset:2048
	ds_read_b128 v[192:195], v144 offset:3072
	s_add_u32 s50, s50, 0x40000
	s_addc_u32 s51, s51, 0
	s_mov_b32 m0, s55
	v_lshl_add_u64 v[238:239], s[50:51], 0, v[136:137]
	ds_read_b128 v[196:199], v149 offset:32768
	ds_read_b128 v[208:211], v149 offset:33792
	ds_read_b128 v[212:215], v149 offset:34816
	ds_read_b128 v[216:219], v149 offset:35840
	ds_read_b128 v[220:223], v149 offset:36864
	ds_read_b128 v[224:227], v149 offset:37888
	ds_read_b128 v[228:231], v149 offset:38912
	ds_read_b128 v[232:235], v149 offset:39936
	global_load_lds_dwordx4 v[238:239], off
	v_lshl_add_u64 v[238:239], s[50:51], 0, v[132:133]
	s_mov_b32 m0, s56
	s_nop 0
	global_load_lds_dwordx4 v[238:239], off
	s_waitcnt vmcnt(8)
	s_waitcnt lgkmcnt(0)
	s_barrier
	v_mfma_f32_16x16x32_bf16 v[126:129], v[150:153], v[196:199], v[126:129]
	v_mfma_f32_16x16x32_bf16 v[122:125], v[158:161], v[196:199], v[122:125]
	v_mfma_f32_16x16x32_bf16 v[114:117], v[150:153], v[212:215], v[114:117]
	v_mfma_f32_16x16x32_bf16 v[106:109], v[158:161], v[212:215], v[106:109]
	v_mfma_f32_16x16x32_bf16 v[98:101], v[150:153], v[220:223], v[98:101]
	v_mfma_f32_16x16x32_bf16 v[90:93], v[158:161], v[220:223], v[90:93]
	v_mfma_f32_16x16x32_bf16 v[82:85], v[150:153], v[228:231], v[82:85]
	v_mfma_f32_16x16x32_bf16 v[72:75], v[158:161], v[228:231], v[72:75]
	v_mfma_f32_16x16x32_bf16 v[126:129], v[154:157], v[208:211], v[126:129]
	v_mfma_f32_16x16x32_bf16 v[122:125], v[176:179], v[208:211], v[122:125]
	v_mfma_f32_16x16x32_bf16 v[114:117], v[154:157], v[216:219], v[114:117]
	v_mfma_f32_16x16x32_bf16 v[106:109], v[176:179], v[216:219], v[106:109]
	v_mfma_f32_16x16x32_bf16 v[98:101], v[154:157], v[224:227], v[98:101]
	v_mfma_f32_16x16x32_bf16 v[90:93], v[176:179], v[224:227], v[90:93]
	v_mfma_f32_16x16x32_bf16 v[82:85], v[154:157], v[232:235], v[82:85]
	v_mfma_f32_16x16x32_bf16 v[72:75], v[176:179], v[232:235], v[72:75]
	v_mfma_f32_16x16x32_bf16 v[118:121], v[180:183], v[196:199], v[118:121]
	v_mfma_f32_16x16x32_bf16 v[110:113], v[188:191], v[196:199], v[110:113]
	v_mfma_f32_16x16x32_bf16 v[102:105], v[180:183], v[212:215], v[102:105]
	v_mfma_f32_16x16x32_bf16 v[94:97], v[188:191], v[212:215], v[94:97]
	v_mfma_f32_16x16x32_bf16 v[86:89], v[180:183], v[220:223], v[86:89]
	v_mfma_f32_16x16x32_bf16 v[76:79], v[188:191], v[220:223], v[76:79]
	v_mfma_f32_16x16x32_bf16 v[68:71], v[180:183], v[228:231], v[68:71]
	v_mfma_f32_16x16x32_bf16 v[64:67], v[188:191], v[228:231], v[64:67]
	v_mfma_f32_16x16x32_bf16 v[118:121], v[184:187], v[208:211], v[118:121]
	v_mfma_f32_16x16x32_bf16 v[110:113], v[192:195], v[208:211], v[110:113]
	v_mfma_f32_16x16x32_bf16 v[102:105], v[184:187], v[216:219], v[102:105]
	v_mfma_f32_16x16x32_bf16 v[94:97], v[192:195], v[216:219], v[94:97]
	v_mfma_f32_16x16x32_bf16 v[86:89], v[184:187], v[224:227], v[86:89]
	v_mfma_f32_16x16x32_bf16 v[76:79], v[192:195], v[224:227], v[76:79]
	v_mfma_f32_16x16x32_bf16 v[68:71], v[184:187], v[232:235], v[68:71]
	v_mfma_f32_16x16x32_bf16 v[64:67], v[192:195], v[232:235], v[64:67]
	s_barrier
; #define PG8_STAGE(bufoff, gbase, voff) do { _Pragma("unroll") for (int _i = 0; _i < 2; ++_i) \
;         __builtin_amdgcn_global_load_lds((const unsigned*)((const char*)(gbase) + (voff)[_i]), (PG8_LAS unsigned*)(lds + (bufoff) + ldsw + _i * 8192), 16, 0, 0); } while (0)
; #define PG8_LDA(dst, b, h) do { _Pragma("unroll") for (int m = 0; m < 4; ++m) _Pragma("unroll") for (int k = 0; k < 2; ++k) dst[m][k] = *(const PG8_LAS bf16x8*)(lds + PG8_SA(b, h) + aoff + m * 2048 + k * 1024); } while (0)
; #define PG8_MMA(ai, bj, At, Bt) do { __builtin_amdgcn_s_setprio(1); _Pragma("unroll") for (int m = 0; m < 4; ++m) _Pragma("unroll") for (int n = 0; n < 2; ++n) _Pragma("unroll") for (int k = 0; k < 2; ++k) \
;         acc[ai][bj][m][n] = __builtin_amdgcn_mfma_f32_16x16x32_bf16(Bt[n][k], At[m][k], acc[ai][bj][m][n], 0, 0, 0); __builtin_amdgcn_s_setprio(0); } while (0)
; #define PG8_WAIT_V(n) asm volatile("s_waitcnt vmcnt(" #n ")" ::: "memory")
; #define PG8_WAIT_L(n) asm volatile("s_waitcnt lgkmcnt(" #n ")" ::: "memory")
; #define PG8_BAR __builtin_amdgcn_s_barrier()
; #define PG8_SCHED __builtin_amdgcn_sched_barrier(0)
; template <class Epi, class Sched, bool ALIGN_EPI = false, bool SP2 = false>
; __device__ __forceinline__ void gemm_phase(PG8_LAS unsigned char* lds, const Gemm g, const Sched& S, const Epi& E) {
;     ...
;             PG8_LDA(At, 1, 1); PG8_STAGE(PG8_SB(1, 0), b3, voffB); PG8_STAGE(PG8_SB(1, 1), b3 + hstep, voffB); PG8_STAGE(PG8_SA(1, 0), a3, voffA);
;             PG8_WAIT_V(8); PG8_WAIT_L(0); PG8_BAR; PG8_MMA(1, 0, At, B0); PG8_MMA(1, 1, At, B1); PG8_BAR; PG8_SCHED;
;     ...
;         }
;         if constexpr (ALIGN_EPI) { if (wr == 0) PG8_BAR; }
	s_add_i32 s50, s69, s52
	v_lshl_add_u64 v[142:143], v[142:143], 0, s[40:41]
	s_mov_b32 m0, s50
	ds_read_b128 v[196:199], v149 offset:49152
	ds_read_b128 v[208:211], v149 offset:50176
	ds_read_b128 v[212:215], v149 offset:51200
	ds_read_b128 v[216:219], v149 offset:52224
	ds_read_b128 v[220:223], v149 offset:53248
	ds_read_b128 v[224:227], v149 offset:54272
	ds_read_b128 v[228:231], v149 offset:55296
	ds_read_b128 v[232:235], v149 offset:56320
	global_load_lds_dwordx4 v[142:143], off
	s_add_i32 m0, s50, 0x2000
	s_add_u32 s48, s48, 0x40080
	v_lshl_add_u64 v[142:143], v[146:147], 0, s[40:41]
	s_addc_u32 s49, s49, 0
	s_add_i32 s50, s70, s52
	global_load_lds_dwordx4 v[142:143], off
	v_lshl_add_u64 v[142:143], s[48:49], 0, v[134:135]
	s_mov_b32 m0, s50
	s_nop 0
	global_load_lds_dwordx4 v[142:143], off
	v_lshl_add_u64 v[142:143], s[48:49], 0, v[130:131]
	s_add_i32 m0, s50, 0x2000
	s_nop 0
	global_load_lds_dwordx4 v[142:143], off
	v_lshl_add_u64 v[142:143], v[200:201], 0, s[40:41]
	s_mov_b32 m0, s59
	s_nop 0
	global_load_lds_dwordx4 v[142:143], off
	v_lshl_add_u64 v[142:143], v[236:237], 0, s[40:41]
	s_mov_b32 m0, s60
	s_nop 0
	global_load_lds_dwordx4 v[142:143], off
	s_waitcnt vmcnt(8)
	s_waitcnt lgkmcnt(0)
	s_barrier
	v_mfma_f32_16x16x32_bf16 v[60:63], v[150:153], v[196:199], v[60:63]
	v_mfma_f32_16x16x32_bf16 v[56:59], v[158:161], v[196:199], v[56:59]
	v_mfma_f32_16x16x32_bf16 v[48:51], v[150:153], v[212:215], v[48:51]
	v_mfma_f32_16x16x32_bf16 v[40:43], v[158:161], v[212:215], v[40:43]
	v_mfma_f32_16x16x32_bf16 v[32:35], v[150:153], v[220:223], v[32:35]
	v_mfma_f32_16x16x32_bf16 v[24:27], v[158:161], v[220:223], v[24:27]
	v_mfma_f32_16x16x32_bf16 v[16:19], v[150:153], v[228:231], v[16:19]
	v_mfma_f32_16x16x32_bf16 v[8:11], v[158:161], v[228:231], v[8:11]
	v_mfma_f32_16x16x32_bf16 v[60:63], v[154:157], v[208:211], v[60:63]
	v_mfma_f32_16x16x32_bf16 v[56:59], v[176:179], v[208:211], v[56:59]
	v_mfma_f32_16x16x32_bf16 v[48:51], v[154:157], v[216:219], v[48:51]
	v_mfma_f32_16x16x32_bf16 v[40:43], v[176:179], v[216:219], v[40:43]
	v_mfma_f32_16x16x32_bf16 v[32:35], v[154:157], v[224:227], v[32:35]
	v_mfma_f32_16x16x32_bf16 v[24:27], v[176:179], v[224:227], v[24:27]
	v_mfma_f32_16x16x32_bf16 v[16:19], v[154:157], v[232:235], v[16:19]
	v_mfma_f32_16x16x32_bf16 v[8:11], v[176:179], v[232:235], v[8:11]
	v_mfma_f32_16x16x32_bf16 v[52:55], v[180:183], v[196:199], v[52:55]
	v_mfma_f32_16x16x32_bf16 v[44:47], v[188:191], v[196:199], v[44:47]
	v_mfma_f32_16x16x32_bf16 v[36:39], v[180:183], v[212:215], v[36:39]
	v_mfma_f32_16x16x32_bf16 v[28:31], v[188:191], v[212:215], v[28:31]
	v_mfma_f32_16x16x32_bf16 v[20:23], v[180:183], v[220:223], v[20:23]
	v_mfma_f32_16x16x32_bf16 v[12:15], v[188:191], v[220:223], v[12:15]
	v_mfma_f32_16x16x32_bf16 v[4:7], v[180:183], v[228:231], v[4:7]
	v_mfma_f32_16x16x32_bf16 v[0:3], v[188:191], v[228:231], v[0:3]
	v_mfma_f32_16x16x32_bf16 v[52:55], v[184:187], v[208:211], v[52:55]
	v_mfma_f32_16x16x32_bf16 v[44:47], v[192:195], v[208:211], v[44:47]
	v_mfma_f32_16x16x32_bf16 v[36:39], v[184:187], v[216:219], v[36:39]
	v_mfma_f32_16x16x32_bf16 v[28:31], v[192:195], v[216:219], v[28:31]
	v_mfma_f32_16x16x32_bf16 v[20:23], v[184:187], v[224:227], v[20:23]
	v_mfma_f32_16x16x32_bf16 v[12:15], v[192:195], v[224:227], v[12:15]
	v_mfma_f32_16x16x32_bf16 v[4:7], v[184:187], v[232:235], v[4:7]
	v_mfma_f32_16x16x32_bf16 v[0:3], v[192:195], v[232:235], v[0:3]
	s_barrier
	s_add_i32 s68, s68, 2
	s_add_u32 s46, s46, 0x100
	s_addc_u32 s47, s47, 0
	s_add_u32 s66, s66, 0x100
	s_addc_u32 s67, s67, 0
	s_cmp_gt_u32 s68, 13
	s_cbranch_scc0 .LBB0_129
	s_setprio 0
	s_and_b64 vcc, exec, s[14:15]
	s_cbranch_vccz .LBB0_132
	s_barrier

; #define PG8_STAGE(bufoff, gbase, voff) do { _Pragma("unroll") for (int _i = 0; _i < 2; ++_i) \
;         __builtin_amdgcn_global_load_lds((const unsigned*)((const char*)(gbase) + (voff)[_i]), (PG8_LAS unsigned*)(lds + (bufoff) + ldsw + _i * 8192), 16, 0, 0); } while (0)
; #define PG8_LDA(dst, b, h) do { _Pragma("unroll") for (int m = 0; m < 4; ++m) _Pragma("unroll") for (int k = 0; k < 2; ++k) dst[m][k] = *(const PG8_LAS bf16x8*)(lds + PG8_SA(b, h) + aoff + m * 2048 + k * 1024); } while (0)
; #define PG8_LDB(dst, b, h) do { _Pragma("unroll") for (int n = 0; n < 2; ++n) _Pragma("unroll") for (int k = 0; k < 2; ++k) dst[n][k] = *(const PG8_LAS bf16x8*)(lds + PG8_SB(b, h) + boff + n * 2048 + k * 1024); } while (0)
; #define PG8_WAIT_V(n) asm volatile("s_waitcnt vmcnt(" #n ")" ::: "memory")
; template <class Epi, class Sched, bool ALIGN_EPI = false, bool SP2 = false>
; __device__ __forceinline__ void gemm_phase(PG8_LAS unsigned char* lds, const Gemm g, const Sched& S, const Epi& E) {
;     ...
;         const char* nA = has_next ? (const char*)(nxt.sw ? g.A2 : g.A) + (size_t)nxt.pm * tstep : cA; const char* nB = has_next ? (const char*)(nxt.sw ? g.Bt2 : g.Bt) + (size_t)nxt.pn * tstep : cB;
;         for (int t = 0; t < nt; t += 2) {
;             if constexpr (Epi::PF_TRIPS > 0) { if (t == nt - 2 * Epi::PF_TRIPS) E.prefetch(cur, tid, lds + STAGE_BYTES + wid * 512); }
;             const bool last = (t == nt - 2);
;             const char* a1 = cA + (size_t)(t + 1) * kstep;
;             const char* a2 = last ? nA : cA + (size_t)(t + 2) * kstep; const char* b2 = last ? nB : cB + (size_t)(t + 2) * kstep;
;             const char* a3 = a2 + kstep; const char* b3 = b2 + kstep;
;             if (last && has_next) S.a_ready(nxt);
;             if constexpr (SP2) {
;             PG8_LDB(B0, 0, 0); PG8_LDB(B1, 0, 1); PG8_SCHED; PG8_LDA(At, 0, 0); PG8_STAGE(PG8_SA(1, 1), a1 + hstep, voffA);
;             PG8_WAIT_V(8); PG8_WAIT_L(0); PG8_BAR; PG8_MMA(0, 0, At, B0); PG8_MMA(0, 1, At, B1); PG8_BAR; PG8_SCHED;
;     ...
; #pragma unroll
;         for (int a = 0; a < 2; ++a)
; #pragma unroll
;             for (int b = 0; b < 2; ++b)
; #pragma unroll
;                 for (int m = 0; m < 4; ++m)
; #pragma unroll
;                     for (int n = 0; n < 2; ++n) acc[a][b][m][n] = (f32x4){0.f, 0.f, 0.f, 0.f};
;         cur = nxt; cA = nA; cB = nB; ++ui;
.LBB0_158:
	s_ashr_i32 s17, s16, 31
	s_lshl_b64 s[44:45], s[16:17], 19
	s_cmp_eq_u32 s65, 0
	s_cselect_b32 s17, s30, s52
	s_cselect_b32 s5, s31, s53
	s_cselect_b32 s50, s38, s30
	s_cselect_b32 s51, s39, s31
	s_add_u32 s44, s17, s44
	s_addc_u32 s45, s5, s45
	s_and_b64 s[46:47], s[42:43], exec
	s_cselect_b32 s5, s45, s7
	s_cselect_b32 s17, s44, s6
	s_ashr_i32 s19, s18, 31
	s_lshl_b64 s[46:47], s[18:19], 19
	s_add_u32 s46, s50, s46
	s_addc_u32 s47, s51, s47
	s_and_b64 s[50:51], s[42:43], exec
	s_cselect_b32 s19, s47, s49
	s_cselect_b32 s67, s46, s48
	s_add_u32 s6, s6, 0x40080
	s_addc_u32 s7, s7, 0
	s_add_u32 s68, s48, 0x100
	v_mov_b32_e32 v0, 0
	s_addc_u32 s69, s49, 0
	s_mov_b32 s70, -2
	v_mov_b32_e32 v1, v0
	v_mov_b32_e32 v2, v0
	v_mov_b32_e32 v3, v0
	v_mov_b32_e32 v4, v0
	v_mov_b32_e32 v5, v0
	v_mov_b32_e32 v6, v0
	v_mov_b32_e32 v7, v0
	v_mov_b32_e32 v16, v0
	v_mov_b32_e32 v17, v0
	v_mov_b32_e32 v18, v0
	v_mov_b32_e32 v19, v0
	v_mov_b32_e32 v20, v0
	v_mov_b32_e32 v21, v0
	v_mov_b32_e32 v22, v0
	v_mov_b32_e32 v23, v0
	v_mov_b32_e32 v32, v0
	v_mov_b32_e32 v33, v0
	v_mov_b32_e32 v34, v0
	v_mov_b32_e32 v35, v0
	v_mov_b32_e32 v36, v0
	v_mov_b32_e32 v37, v0
	v_mov_b32_e32 v38, v0
	v_mov_b32_e32 v39, v0
	v_mov_b32_e32 v48, v0
	v_mov_b32_e32 v49, v0
	v_mov_b32_e32 v50, v0
	v_mov_b32_e32 v51, v0
	v_mov_b32_e32 v52, v0
	v_mov_b32_e32 v53, v0
	v_mov_b32_e32 v54, v0
	v_mov_b32_e32 v55, v0
	v_mov_b32_e32 v8, v0
	v_mov_b32_e32 v9, v0
	v_mov_b32_e32 v10, v0
	v_mov_b32_e32 v11, v0
	v_mov_b32_e32 v12, v0
	v_mov_b32_e32 v13, v0
	v_mov_b32_e32 v14, v0
	v_mov_b32_e32 v15, v0
	v_mov_b32_e32 v24, v0
	v_mov_b32_e32 v25, v0
	v_mov_b32_e32 v26, v0
	v_mov_b32_e32 v27, v0
	v_mov_b32_e32 v28, v0
	v_mov_b32_e32 v29, v0
	v_mov_b32_e32 v30, v0
	v_mov_b32_e32 v31, v0
	v_mov_b32_e32 v40, v0
	v_mov_b32_e32 v41, v0
	v_mov_b32_e32 v42, v0
	v_mov_b32_e32 v43, v0
	v_mov_b32_e32 v44, v0
	v_mov_b32_e32 v45, v0
	v_mov_b32_e32 v46, v0
	v_mov_b32_e32 v47, v0
	v_mov_b32_e32 v56, v0
	v_mov_b32_e32 v57, v0
	v_mov_b32_e32 v58, v0
	v_mov_b32_e32 v59, v0
	v_mov_b32_e32 v60, v0
	v_mov_b32_e32 v61, v0
	v_mov_b32_e32 v62, v0
	v_mov_b32_e32 v63, v0
	v_mov_b32_e32 v64, v0
	v_mov_b32_e32 v65, v0
	v_mov_b32_e32 v66, v0
	v_mov_b32_e32 v67, v0
	v_mov_b32_e32 v68, v0
	v_mov_b32_e32 v69, v0
	v_mov_b32_e32 v70, v0
	v_mov_b32_e32 v71, v0
	v_mov_b32_e32 v82, v0
	v_mov_b32_e32 v83, v0
	v_mov_b32_e32 v84, v0
	v_mov_b32_e32 v85, v0
	v_mov_b32_e32 v86, v0
	v_mov_b32_e32 v87, v0
	v_mov_b32_e32 v88, v0
	v_mov_b32_e32 v89, v0
	v_mov_b32_e32 v98, v0
	v_mov_b32_e32 v99, v0
	v_mov_b32_e32 v100, v0
	v_mov_b32_e32 v101, v0
	v_mov_b32_e32 v102, v0
	v_mov_b32_e32 v103, v0
	v_mov_b32_e32 v104, v0
	v_mov_b32_e32 v105, v0
	v_mov_b32_e32 v114, v0
	v_mov_b32_e32 v115, v0
	v_mov_b32_e32 v116, v0
	v_mov_b32_e32 v117, v0
	v_mov_b32_e32 v118, v0
	v_mov_b32_e32 v119, v0
	v_mov_b32_e32 v120, v0
	v_mov_b32_e32 v121, v0
	v_mov_b32_e32 v72, v0
	v_mov_b32_e32 v73, v0
	v_mov_b32_e32 v74, v0
	v_mov_b32_e32 v75, v0
	v_mov_b32_e32 v76, v0
	v_mov_b32_e32 v77, v0
	v_mov_b32_e32 v78, v0
	v_mov_b32_e32 v79, v0
	v_mov_b32_e32 v90, v0
	v_mov_b32_e32 v91, v0
	v_mov_b32_e32 v92, v0
	v_mov_b32_e32 v93, v0
	v_mov_b32_e32 v94, v0
	v_mov_b32_e32 v95, v0
	v_mov_b32_e32 v96, v0
	v_mov_b32_e32 v97, v0
	v_mov_b32_e32 v106, v0
	v_mov_b32_e32 v107, v0
	v_mov_b32_e32 v108, v0
	v_mov_b32_e32 v109, v0
	v_mov_b32_e32 v110, v0
	v_mov_b32_e32 v111, v0
	v_mov_b32_e32 v112, v0
	v_mov_b32_e32 v113, v0
	v_mov_b32_e32 v122, v0
	v_mov_b32_e32 v123, v0
	v_mov_b32_e32 v124, v0
	v_mov_b32_e32 v125, v0
	v_mov_b32_e32 v126, v0
	v_mov_b32_e32 v127, v0
	v_mov_b32_e32 v128, v0
	v_mov_b32_e32 v129, v0
	v_readfirstlane_b32 s100, v202
	s_nop 3
	s_lshr_b32 s100, s100, 8
	s_cmp_eq_u32 s100, 0
	s_cbranch_scc1 .Lsp_qkv
	s_setprio 1
.Lsp_qkv:
.LBB0_159:
	s_add_u32 s48, s6, 0xfffc0080
	s_addc_u32 s49, s7, -1
	s_add_i32 s71, 0, 0x10000
	s_cmp_eq_u32 s70, 12
	s_cselect_b32 s51, s5, s49
	s_cselect_b32 s50, s17, s48
	s_cselect_b32 s49, s19, s69
	s_cselect_b32 s48, s67, s68
	s_add_i32 s74, 0, 0x14000
	v_add_u32_e32 v142, s71, v199
	v_add_u32_e32 v158, s74, v199
	ds_read_b128 v[130:133], v142
	ds_read_b128 v[134:137], v142 offset:1024
	ds_read_b128 v[138:141], v142 offset:2048
	s_waitcnt lgkmcnt(0)
	ds_read_b128 v[142:145], v142 offset:3072
	ds_read_b128 v[146:149], v158
	ds_read_b128 v[150:153], v158 offset:1024
	ds_read_b128 v[154:157], v158 offset:2048
	ds_read_b128 v[158:161], v158 offset:3072
	v_lshl_add_u64 v[196:197], s[6:7], 0, v[184:185]
	s_add_i32 m0, s11, 0xc000
	ds_read_b128 v[188:191], v200
	ds_read_b128 v[192:195], v200 offset:1024
	ds_read_b128 v[208:211], v200 offset:2048
	ds_read_b128 v[212:215], v200 offset:3072
	ds_read_b128 v[216:219], v200 offset:4096
	ds_read_b128 v[220:223], v200 offset:5120
	ds_read_b128 v[224:227], v200 offset:6144
	ds_read_b128 v[228:231], v200 offset:7168
	global_load_lds_dwordx4 v[196:197], off
	v_lshl_add_u64 v[196:197], s[6:7], 0, v[186:187]
	s_add_i32 m0, s11, 0xe000
	s_nop 0
	global_load_lds_dwordx4 v[196:197], off
	s_waitcnt vmcnt(8)
	s_waitcnt lgkmcnt(0)
	s_barrier
; #define PG8_STAGE(bufoff, gbase, voff) do { _Pragma("unroll") for (int _i = 0; _i < 2; ++_i) \
;         __builtin_amdgcn_global_load_lds((const unsigned*)((const char*)(gbase) + (voff)[_i]), (PG8_LAS unsigned*)(lds + (bufoff) + ldsw + _i * 8192), 16, 0, 0); } while (0)
; #define PG8_LDA(dst, b, h) do { _Pragma("unroll") for (int m = 0; m < 4; ++m) _Pragma("unroll") for (int k = 0; k < 2; ++k) dst[m][k] = *(const PG8_LAS bf16x8*)(lds + PG8_SA(b, h) + aoff + m * 2048 + k * 1024); } while (0)
; #define PG8_MMA(ai, bj, At, Bt) do { __builtin_amdgcn_s_setprio(1); _Pragma("unroll") for (int m = 0; m < 4; ++m) _Pragma("unroll") for (int n = 0; n < 2; ++n) _Pragma("unroll") for (int k = 0; k < 2; ++k) \
;         acc[ai][bj][m][n] = __builtin_amdgcn_mfma_f32_16x16x32_bf16(Bt[n][k], At[m][k], acc[ai][bj][m][n], 0, 0, 0); __builtin_amdgcn_s_setprio(0); } while (0)
; #define PG8_WAIT_V(n) asm volatile("s_waitcnt vmcnt(" #n ")" ::: "memory")
; #define PG8_WAIT_L(n) asm volatile("s_waitcnt lgkmcnt(" #n ")" ::: "memory")
; #define PG8_BAR __builtin_amdgcn_s_barrier()
; #define PG8_SCHED __builtin_amdgcn_sched_barrier(0)
; template <class Epi, class Sched, bool ALIGN_EPI = false, bool SP2 = false>
; __device__ __forceinline__ void gemm_phase(PG8_LAS unsigned char* lds, const Gemm g, const Sched& S, const Epi& E) {
;     ...
;             PG8_WAIT_V(8); PG8_WAIT_L(0); PG8_BAR; PG8_MMA(0, 0, At, B0); PG8_MMA(0, 1, At, B1); PG8_BAR; PG8_SCHED;
;             PG8_LDA(At, 0, 1); PG8_STAGE(PG8_SB(0, 0), b2, voffB); PG8_STAGE(PG8_SB(0, 1), b2 + hstep, voffB); PG8_STAGE(PG8_SA(0, 0), a2, voffA);
;             PG8_WAIT_V(8); PG8_WAIT_L(0); PG8_BAR; PG8_MMA(1, 0, At, B0); PG8_MMA(1, 1, At, B1); PG8_BAR; PG8_SCHED;
	v_mfma_f32_16x16x32_bf16 v[126:129], v[130:133], v[188:191], v[126:129]
	v_mfma_f32_16x16x32_bf16 v[122:125], v[138:141], v[188:191], v[122:125]
	v_mfma_f32_16x16x32_bf16 v[110:113], v[130:133], v[208:211], v[110:113]
	v_mfma_f32_16x16x32_bf16 v[106:109], v[138:141], v[208:211], v[106:109]
	v_mfma_f32_16x16x32_bf16 v[94:97], v[130:133], v[216:219], v[94:97]
	v_mfma_f32_16x16x32_bf16 v[90:93], v[138:141], v[216:219], v[90:93]
	v_mfma_f32_16x16x32_bf16 v[76:79], v[130:133], v[224:227], v[76:79]
	v_mfma_f32_16x16x32_bf16 v[72:75], v[138:141], v[224:227], v[72:75]
	v_mfma_f32_16x16x32_bf16 v[126:129], v[134:137], v[192:195], v[126:129]
	v_mfma_f32_16x16x32_bf16 v[122:125], v[142:145], v[192:195], v[122:125]
	v_mfma_f32_16x16x32_bf16 v[110:113], v[134:137], v[212:215], v[110:113]
	v_mfma_f32_16x16x32_bf16 v[106:109], v[142:145], v[212:215], v[106:109]
	v_mfma_f32_16x16x32_bf16 v[94:97], v[134:137], v[220:223], v[94:97]
	v_mfma_f32_16x16x32_bf16 v[90:93], v[142:145], v[220:223], v[90:93]
	v_mfma_f32_16x16x32_bf16 v[76:79], v[134:137], v[228:231], v[76:79]
	v_mfma_f32_16x16x32_bf16 v[72:75], v[142:145], v[228:231], v[72:75]
	v_mfma_f32_16x16x32_bf16 v[118:121], v[146:149], v[188:191], v[118:121]
	v_mfma_f32_16x16x32_bf16 v[114:117], v[154:157], v[188:191], v[114:117]
	v_mfma_f32_16x16x32_bf16 v[102:105], v[146:149], v[208:211], v[102:105]
	v_mfma_f32_16x16x32_bf16 v[98:101], v[154:157], v[208:211], v[98:101]
	v_mfma_f32_16x16x32_bf16 v[86:89], v[146:149], v[216:219], v[86:89]
	v_mfma_f32_16x16x32_bf16 v[82:85], v[154:157], v[216:219], v[82:85]
	v_mfma_f32_16x16x32_bf16 v[68:71], v[146:149], v[224:227], v[68:71]
	v_mfma_f32_16x16x32_bf16 v[64:67], v[154:157], v[224:227], v[64:67]
	v_mfma_f32_16x16x32_bf16 v[118:121], v[150:153], v[192:195], v[118:121]
	v_mfma_f32_16x16x32_bf16 v[114:117], v[158:161], v[192:195], v[114:117]
	v_mfma_f32_16x16x32_bf16 v[102:105], v[150:153], v[212:215], v[102:105]
	v_mfma_f32_16x16x32_bf16 v[98:101], v[158:161], v[212:215], v[98:101]
	v_mfma_f32_16x16x32_bf16 v[86:89], v[150:153], v[220:223], v[86:89]
	v_mfma_f32_16x16x32_bf16 v[82:85], v[158:161], v[220:223], v[82:85]
	v_mfma_f32_16x16x32_bf16 v[68:71], v[150:153], v[228:231], v[68:71]
	v_mfma_f32_16x16x32_bf16 v[64:67], v[158:161], v[228:231], v[64:67]
	s_barrier
	s_add_i32 s71, s71, s54
	v_lshl_add_u64 v[196:197], s[48:49], 0, v[178:179]
	s_mov_b32 m0, s71
	ds_read_b128 v[188:191], v200 offset:16384
	ds_read_b128 v[192:195], v200 offset:17408
	ds_read_b128 v[208:211], v200 offset:18432
	ds_read_b128 v[212:215], v200 offset:19456
	ds_read_b128 v[216:219], v200 offset:20480
	ds_read_b128 v[220:223], v200 offset:21504
	ds_read_b128 v[224:227], v200 offset:22528
	ds_read_b128 v[228:231], v200 offset:23552
	global_load_lds_dwordx4 v[196:197], off
	s_add_i32 m0, s71, 0x2000
	s_add_u32 s72, s48, 0x40000
	v_lshl_add_u64 v[232:233], s[48:49], 0, v[182:183]
	s_addc_u32 s73, s49, 0
	s_add_i32 s71, s74, s54
	global_load_lds_dwordx4 v[232:233], off
	v_lshl_add_u64 v[234:235], s[72:73], 0, v[178:179]
	s_mov_b32 m0, s71
	v_lshl_add_u64 v[236:237], s[50:51], 0, v[180:181]
	global_load_lds_dwordx4 v[234:235], off
	v_lshl_add_u64 v[234:235], s[72:73], 0, v[182:183]
	s_add_i32 m0, s71, 0x2000
	s_nop 0
	global_load_lds_dwordx4 v[234:235], off
	v_lshl_add_u64 v[234:235], s[50:51], 0, v[176:177]
	s_mov_b32 m0, s11
	s_nop 0
	global_load_lds_dwordx4 v[234:235], off
	s_mov_b32 m0, s55
	s_nop 0
	global_load_lds_dwordx4 v[236:237], off
	s_waitcnt vmcnt(8)
	s_waitcnt lgkmcnt(0)
	s_barrier
	v_mfma_f32_16x16x32_bf16 v[60:63], v[130:133], v[188:191], v[60:63]
	v_mfma_f32_16x16x32_bf16 v[56:59], v[138:141], v[188:191], v[56:59]
	v_mfma_f32_16x16x32_bf16 v[44:47], v[130:133], v[208:211], v[44:47]
	v_mfma_f32_16x16x32_bf16 v[40:43], v[138:141], v[208:211], v[40:43]
	v_mfma_f32_16x16x32_bf16 v[28:31], v[130:133], v[216:219], v[28:31]
	v_mfma_f32_16x16x32_bf16 v[24:27], v[138:141], v[216:219], v[24:27]
	v_mfma_f32_16x16x32_bf16 v[12:15], v[130:133], v[224:227], v[12:15]
	v_mfma_f32_16x16x32_bf16 v[8:11], v[138:141], v[224:227], v[8:11]
	v_mfma_f32_16x16x32_bf16 v[60:63], v[134:137], v[192:195], v[60:63]
	v_mfma_f32_16x16x32_bf16 v[56:59], v[142:145], v[192:195], v[56:59]
	v_mfma_f32_16x16x32_bf16 v[44:47], v[134:137], v[212:215], v[44:47]
	v_mfma_f32_16x16x32_bf16 v[40:43], v[142:145], v[212:215], v[40:43]
	v_mfma_f32_16x16x32_bf16 v[28:31], v[134:137], v[220:223], v[28:31]
	v_mfma_f32_16x16x32_bf16 v[24:27], v[142:145], v[220:223], v[24:27]
	v_mfma_f32_16x16x32_bf16 v[12:15], v[134:137], v[228:231], v[12:15]
	v_mfma_f32_16x16x32_bf16 v[8:11], v[142:145], v[228:231], v[8:11]
	v_mfma_f32_16x16x32_bf16 v[52:55], v[146:149], v[188:191], v[52:55]
	v_mfma_f32_16x16x32_bf16 v[48:51], v[154:157], v[188:191], v[48:51]
	v_mfma_f32_16x16x32_bf16 v[36:39], v[146:149], v[208:211], v[36:39]
	v_mfma_f32_16x16x32_bf16 v[32:35], v[154:157], v[208:211], v[32:35]
	v_mfma_f32_16x16x32_bf16 v[20:23], v[146:149], v[216:219], v[20:23]
	v_mfma_f32_16x16x32_bf16 v[16:19], v[154:157], v[216:219], v[16:19]
	v_mfma_f32_16x16x32_bf16 v[4:7], v[146:149], v[224:227], v[4:7]
	v_mfma_f32_16x16x32_bf16 v[0:3], v[154:157], v[224:227], v[0:3]
	v_mfma_f32_16x16x32_bf16 v[52:55], v[150:153], v[192:195], v[52:55]
	v_mfma_f32_16x16x32_bf16 v[48:51], v[158:161], v[192:195], v[48:51]
	v_mfma_f32_16x16x32_bf16 v[36:39], v[150:153], v[212:215], v[36:39]
	v_mfma_f32_16x16x32_bf16 v[32:35], v[158:161], v[212:215], v[32:35]
	v_mfma_f32_16x16x32_bf16 v[20:23], v[150:153], v[220:223], v[20:23]
	v_mfma_f32_16x16x32_bf16 v[16:19], v[158:161], v[220:223], v[16:19]
	v_mfma_f32_16x16x32_bf16 v[4:7], v[150:153], v[228:231], v[4:7]
	v_mfma_f32_16x16x32_bf16 v[0:3], v[158:161], v[228:231], v[0:3]
	s_barrier
; #define PG8_STAGE(bufoff, gbase, voff) do { _Pragma("unroll") for (int _i = 0; _i < 2; ++_i) \
;         __builtin_amdgcn_global_load_lds((const unsigned*)((const char*)(gbase) + (voff)[_i]), (PG8_LAS unsigned*)(lds + (bufoff) + ldsw + _i * 8192), 16, 0, 0); } while (0)
; #define PG8_LDA(dst, b, h) do { _Pragma("unroll") for (int m = 0; m < 4; ++m) _Pragma("unroll") for (int k = 0; k < 2; ++k) dst[m][k] = *(const PG8_LAS bf16x8*)(lds + PG8_SA(b, h) + aoff + m * 2048 + k * 1024); } while (0)
; #define PG8_LDB(dst, b, h) do { _Pragma("unroll") for (int n = 0; n < 2; ++n) _Pragma("unroll") for (int k = 0; k < 2; ++k) dst[n][k] = *(const PG8_LAS bf16x8*)(lds + PG8_SB(b, h) + boff + n * 2048 + k * 1024); } while (0)
; #define PG8_MMA(ai, bj, At, Bt) do { __builtin_amdgcn_s_setprio(1); _Pragma("unroll") for (int m = 0; m < 4; ++m) _Pragma("unroll") for (int n = 0; n < 2; ++n) _Pragma("unroll") for (int k = 0; k < 2; ++k) \
;         acc[ai][bj][m][n] = __builtin_amdgcn_mfma_f32_16x16x32_bf16(Bt[n][k], At[m][k], acc[ai][bj][m][n], 0, 0, 0); __builtin_amdgcn_s_setprio(0); } while (0)
; #define PG8_WAIT_V(n) asm volatile("s_waitcnt vmcnt(" #n ")" ::: "memory")
; #define PG8_WAIT_L(n) asm volatile("s_waitcnt lgkmcnt(" #n ")" ::: "memory")
; #define PG8_BAR __builtin_amdgcn_s_barrier()
; #define PG8_SCHED __builtin_amdgcn_sched_barrier(0)
; template <class Epi, class Sched, bool ALIGN_EPI = false, bool SP2 = false>
; __device__ __forceinline__ void gemm_phase(PG8_LAS unsigned char* lds, const Gemm g, const Sched& S, const Epi& E) {
;     ...
;             PG8_LDB(B0, 1, 0); PG8_LDB(B1, 1, 1); PG8_SCHED; PG8_LDA(At, 1, 0); PG8_STAGE(PG8_SA(0, 1), a2 + hstep, voffA);
;             PG8_WAIT_V(8); PG8_WAIT_L(0); PG8_BAR; PG8_MMA(0, 0, At, B0); PG8_MMA(0, 1, At, B1); PG8_BAR; PG8_SCHED;
	s_add_i32 s71, 0, 0x18000
	s_add_i32 s72, 0, 0x1c000
	v_add_u32_e32 v142, s71, v199
	v_add_u32_e32 v158, s72, v199
	ds_read_b128 v[130:133], v142
	ds_read_b128 v[134:137], v142 offset:1024
	ds_read_b128 v[138:141], v142 offset:2048
	ds_read_b128 v[142:145], v142 offset:3072
	ds_read_b128 v[146:149], v158
	ds_read_b128 v[150:153], v158 offset:1024
	ds_read_b128 v[154:157], v158 offset:2048
	ds_read_b128 v[158:161], v158 offset:3072
	s_add_u32 s50, s50, 0x40000
	s_addc_u32 s51, s51, 0
	s_mov_b32 m0, s56
	v_lshl_add_u64 v[238:239], s[50:51], 0, v[176:177]
	ds_read_b128 v[188:191], v200 offset:32768
	ds_read_b128 v[192:195], v200 offset:33792
	ds_read_b128 v[208:211], v200 offset:34816
	ds_read_b128 v[212:215], v200 offset:35840
	ds_read_b128 v[216:219], v200 offset:36864
	ds_read_b128 v[220:223], v200 offset:37888
	ds_read_b128 v[224:227], v200 offset:38912
	ds_read_b128 v[228:231], v200 offset:39936
	global_load_lds_dwordx4 v[238:239], off
	v_lshl_add_u64 v[238:239], s[50:51], 0, v[180:181]
	s_mov_b32 m0, s57
	s_nop 0
	global_load_lds_dwordx4 v[238:239], off
	s_waitcnt vmcnt(8)
	s_waitcnt lgkmcnt(0)
	s_barrier
	v_mfma_f32_16x16x32_bf16 v[126:129], v[130:133], v[188:191], v[126:129]
	v_mfma_f32_16x16x32_bf16 v[122:125], v[138:141], v[188:191], v[122:125]
	v_mfma_f32_16x16x32_bf16 v[110:113], v[130:133], v[208:211], v[110:113]
	v_mfma_f32_16x16x32_bf16 v[106:109], v[138:141], v[208:211], v[106:109]
	v_mfma_f32_16x16x32_bf16 v[94:97], v[130:133], v[216:219], v[94:97]
	v_mfma_f32_16x16x32_bf16 v[90:93], v[138:141], v[216:219], v[90:93]
	v_mfma_f32_16x16x32_bf16 v[76:79], v[130:133], v[224:227], v[76:79]
	v_mfma_f32_16x16x32_bf16 v[72:75], v[138:141], v[224:227], v[72:75]
	v_mfma_f32_16x16x32_bf16 v[126:129], v[134:137], v[192:195], v[126:129]
	v_mfma_f32_16x16x32_bf16 v[122:125], v[142:145], v[192:195], v[122:125]
	v_mfma_f32_16x16x32_bf16 v[110:113], v[134:137], v[212:215], v[110:113]
	v_mfma_f32_16x16x32_bf16 v[106:109], v[142:145], v[212:215], v[106:109]
	v_mfma_f32_16x16x32_bf16 v[94:97], v[134:137], v[220:223], v[94:97]
	v_mfma_f32_16x16x32_bf16 v[90:93], v[142:145], v[220:223], v[90:93]
	v_mfma_f32_16x16x32_bf16 v[76:79], v[134:137], v[228:231], v[76:79]
	v_mfma_f32_16x16x32_bf16 v[72:75], v[142:145], v[228:231], v[72:75]
	v_mfma_f32_16x16x32_bf16 v[118:121], v[146:149], v[188:191], v[118:121]
	v_mfma_f32_16x16x32_bf16 v[114:117], v[154:157], v[188:191], v[114:117]
	v_mfma_f32_16x16x32_bf16 v[102:105], v[146:149], v[208:211], v[102:105]
	v_mfma_f32_16x16x32_bf16 v[98:101], v[154:157], v[208:211], v[98:101]
	v_mfma_f32_16x16x32_bf16 v[86:89], v[146:149], v[216:219], v[86:89]
	v_mfma_f32_16x16x32_bf16 v[82:85], v[154:157], v[216:219], v[82:85]
	v_mfma_f32_16x16x32_bf16 v[68:71], v[146:149], v[224:227], v[68:71]
	v_mfma_f32_16x16x32_bf16 v[64:67], v[154:157], v[224:227], v[64:67]
	v_mfma_f32_16x16x32_bf16 v[118:121], v[150:153], v[192:195], v[118:121]
	v_mfma_f32_16x16x32_bf16 v[114:117], v[158:161], v[192:195], v[114:117]
	v_mfma_f32_16x16x32_bf16 v[102:105], v[150:153], v[212:215], v[102:105]
	v_mfma_f32_16x16x32_bf16 v[98:101], v[158:161], v[212:215], v[98:101]
	v_mfma_f32_16x16x32_bf16 v[86:89], v[150:153], v[220:223], v[86:89]
	v_mfma_f32_16x16x32_bf16 v[82:85], v[158:161], v[220:223], v[82:85]
	v_mfma_f32_16x16x32_bf16 v[68:71], v[150:153], v[228:231], v[68:71]
	v_mfma_f32_16x16x32_bf16 v[64:67], v[158:161], v[228:231], v[64:67]
	s_barrier
; #define PG8_STAGE(bufoff, gbase, voff) do { _Pragma("unroll") for (int _i = 0; _i < 2; ++_i) \
;         __builtin_amdgcn_global_load_lds((const unsigned*)((const char*)(gbase) + (voff)[_i]), (PG8_LAS unsigned*)(lds + (bufoff) + ldsw + _i * 8192), 16, 0, 0); } while (0)
; #define PG8_LDA(dst, b, h) do { _Pragma("unroll") for (int m = 0; m < 4; ++m) _Pragma("unroll") for (int k = 0; k < 2; ++k) dst[m][k] = *(const PG8_LAS bf16x8*)(lds + PG8_SA(b, h) + aoff + m * 2048 + k * 1024); } while (0)
; #define PG8_MMA(ai, bj, At, Bt) do { __builtin_amdgcn_s_setprio(1); _Pragma("unroll") for (int m = 0; m < 4; ++m) _Pragma("unroll") for (int n = 0; n < 2; ++n) _Pragma("unroll") for (int k = 0; k < 2; ++k) \
;         acc[ai][bj][m][n] = __builtin_amdgcn_mfma_f32_16x16x32_bf16(Bt[n][k], At[m][k], acc[ai][bj][m][n], 0, 0, 0); __builtin_amdgcn_s_setprio(0); } while (0)
; #define PG8_WAIT_V(n) asm volatile("s_waitcnt vmcnt(" #n ")" ::: "memory")
; #define PG8_WAIT_L(n) asm volatile("s_waitcnt lgkmcnt(" #n ")" ::: "memory")
; #define PG8_BAR __builtin_amdgcn_s_barrier()
; #define PG8_SCHED __builtin_amdgcn_sched_barrier(0)
; template <class Epi, class Sched, bool ALIGN_EPI = false, bool SP2 = false>
; __device__ __forceinline__ void gemm_phase(PG8_LAS unsigned char* lds, const Gemm g, const Sched& S, const Epi& E) {
;     ...
;             PG8_LDA(At, 1, 1); PG8_STAGE(PG8_SB(1, 0), b3, voffB); PG8_STAGE(PG8_SB(1, 1), b3 + hstep, voffB); PG8_STAGE(PG8_SA(1, 0), a3, voffA);
;             PG8_WAIT_V(8); PG8_WAIT_L(0); PG8_BAR; PG8_MMA(1, 0, At, B0); PG8_MMA(1, 1, At, B1); PG8_BAR; PG8_SCHED;
;     ...
;         }
;         if constexpr (ALIGN_EPI) { if (wr == 0) PG8_BAR; }
	s_add_i32 s50, s71, s54
	v_lshl_add_u64 v[196:197], v[196:197], 0, s[40:41]
	s_mov_b32 m0, s50
	ds_read_b128 v[188:191], v200 offset:49152
	ds_read_b128 v[192:195], v200 offset:50176
	ds_read_b128 v[208:211], v200 offset:51200
	ds_read_b128 v[212:215], v200 offset:52224
	ds_read_b128 v[216:219], v200 offset:53248
	ds_read_b128 v[220:223], v200 offset:54272
	ds_read_b128 v[224:227], v200 offset:55296
	ds_read_b128 v[228:231], v200 offset:56320
	global_load_lds_dwordx4 v[196:197], off
	s_add_i32 m0, s50, 0x2000
	s_add_u32 s48, s48, 0x40080
	v_lshl_add_u64 v[196:197], v[232:233], 0, s[40:41]
	s_addc_u32 s49, s49, 0
	s_add_i32 s50, s72, s54
	global_load_lds_dwordx4 v[196:197], off
	v_lshl_add_u64 v[196:197], s[48:49], 0, v[178:179]
	s_mov_b32 m0, s50
	s_nop 0
	global_load_lds_dwordx4 v[196:197], off
	v_lshl_add_u64 v[196:197], s[48:49], 0, v[182:183]
	s_add_i32 m0, s50, 0x2000
	s_nop 0
	global_load_lds_dwordx4 v[196:197], off
	v_lshl_add_u64 v[196:197], v[234:235], 0, s[40:41]
	s_mov_b32 m0, s61
	s_nop 0
	global_load_lds_dwordx4 v[196:197], off
	v_lshl_add_u64 v[196:197], v[236:237], 0, s[40:41]
	s_mov_b32 m0, s62
	s_nop 0
	global_load_lds_dwordx4 v[196:197], off
	s_waitcnt vmcnt(8)
	s_waitcnt lgkmcnt(0)
	s_barrier
	v_mfma_f32_16x16x32_bf16 v[60:63], v[130:133], v[188:191], v[60:63]
	v_mfma_f32_16x16x32_bf16 v[56:59], v[138:141], v[188:191], v[56:59]
	v_mfma_f32_16x16x32_bf16 v[44:47], v[130:133], v[208:211], v[44:47]
	v_mfma_f32_16x16x32_bf16 v[40:43], v[138:141], v[208:211], v[40:43]
	v_mfma_f32_16x16x32_bf16 v[28:31], v[130:133], v[216:219], v[28:31]
	v_mfma_f32_16x16x32_bf16 v[24:27], v[138:141], v[216:219], v[24:27]
	v_mfma_f32_16x16x32_bf16 v[12:15], v[130:133], v[224:227], v[12:15]
	v_mfma_f32_16x16x32_bf16 v[8:11], v[138:141], v[224:227], v[8:11]
	v_mfma_f32_16x16x32_bf16 v[60:63], v[134:137], v[192:195], v[60:63]
	v_mfma_f32_16x16x32_bf16 v[56:59], v[142:145], v[192:195], v[56:59]
	v_mfma_f32_16x16x32_bf16 v[44:47], v[134:137], v[212:215], v[44:47]
	v_mfma_f32_16x16x32_bf16 v[40:43], v[142:145], v[212:215], v[40:43]
	v_mfma_f32_16x16x32_bf16 v[28:31], v[134:137], v[220:223], v[28:31]
	v_mfma_f32_16x16x32_bf16 v[24:27], v[142:145], v[220:223], v[24:27]
	v_mfma_f32_16x16x32_bf16 v[12:15], v[134:137], v[228:231], v[12:15]
	v_mfma_f32_16x16x32_bf16 v[8:11], v[142:145], v[228:231], v[8:11]
	v_mfma_f32_16x16x32_bf16 v[52:55], v[146:149], v[188:191], v[52:55]
	v_mfma_f32_16x16x32_bf16 v[48:51], v[154:157], v[188:191], v[48:51]
	v_mfma_f32_16x16x32_bf16 v[36:39], v[146:149], v[208:211], v[36:39]
	v_mfma_f32_16x16x32_bf16 v[32:35], v[154:157], v[208:211], v[32:35]
	v_mfma_f32_16x16x32_bf16 v[20:23], v[146:149], v[216:219], v[20:23]
	v_mfma_f32_16x16x32_bf16 v[16:19], v[154:157], v[216:219], v[16:19]
	v_mfma_f32_16x16x32_bf16 v[4:7], v[146:149], v[224:227], v[4:7]
	v_mfma_f32_16x16x32_bf16 v[0:3], v[154:157], v[224:227], v[0:3]
	v_mfma_f32_16x16x32_bf16 v[52:55], v[150:153], v[192:195], v[52:55]
	v_mfma_f32_16x16x32_bf16 v[48:51], v[158:161], v[192:195], v[48:51]
	v_mfma_f32_16x16x32_bf16 v[36:39], v[150:153], v[212:215], v[36:39]
	v_mfma_f32_16x16x32_bf16 v[32:35], v[158:161], v[212:215], v[32:35]
	v_mfma_f32_16x16x32_bf16 v[20:23], v[150:153], v[220:223], v[20:23]
	v_mfma_f32_16x16x32_bf16 v[16:19], v[158:161], v[220:223], v[16:19]
	v_mfma_f32_16x16x32_bf16 v[4:7], v[150:153], v[228:231], v[4:7]
	v_mfma_f32_16x16x32_bf16 v[0:3], v[158:161], v[228:231], v[0:3]
	s_barrier
	s_add_i32 s70, s70, 2
	s_add_u32 s6, s6, 0x100
	s_addc_u32 s7, s7, 0
	s_add_u32 s68, s68, 0x100
	s_addc_u32 s69, s69, 0
	s_cmp_gt_u32 s70, 13
	s_cbranch_scc0 .LBB0_159
	s_setprio 0
	s_and_b64 vcc, exec, s[14:15]
	s_cbranch_vccz .LBB0_162
	s_barrier

; #define PG8_STAGE(bufoff, gbase, voff) do { _Pragma("unroll") for (int _i = 0; _i < 2; ++_i) \
;         __builtin_amdgcn_global_load_lds((const unsigned*)((const char*)(gbase) + (voff)[_i]), (PG8_LAS unsigned*)(lds + (bufoff) + ldsw + _i * 8192), 16, 0, 0); } while (0)
; #define PG8_LDA(dst, b, h) do { _Pragma("unroll") for (int m = 0; m < 4; ++m) _Pragma("unroll") for (int k = 0; k < 2; ++k) dst[m][k] = *(const PG8_LAS bf16x8*)(lds + PG8_SA(b, h) + aoff + m * 2048 + k * 1024); } while (0)
; #define PG8_LDB(dst, b, h) do { _Pragma("unroll") for (int n = 0; n < 2; ++n) _Pragma("unroll") for (int k = 0; k < 2; ++k) dst[n][k] = *(const PG8_LAS bf16x8*)(lds + PG8_SB(b, h) + boff + n * 2048 + k * 1024); } while (0)
; #define PG8_WAIT_V(n) asm volatile("s_waitcnt vmcnt(" #n ")" ::: "memory")
; template <class Epi, class Sched, bool ALIGN_EPI = false, bool SP2 = false>
; __device__ __forceinline__ void gemm_phase(PG8_LAS unsigned char* lds, const Gemm g, const Sched& S, const Epi& E) {
;     ...
;         const char* nA = has_next ? (const char*)(nxt.sw ? g.A2 : g.A) + (size_t)nxt.pm * tstep : cA; const char* nB = has_next ? (const char*)(nxt.sw ? g.Bt2 : g.Bt) + (size_t)nxt.pn * tstep : cB;
;         for (int t = 0; t < nt; t += 2) {
;             if constexpr (Epi::PF_TRIPS > 0) { if (t == nt - 2 * Epi::PF_TRIPS) E.prefetch(cur, tid, lds + STAGE_BYTES + wid * 512); }
;             const bool last = (t == nt - 2);
;             const char* a1 = cA + (size_t)(t + 1) * kstep;
;             const char* a2 = last ? nA : cA + (size_t)(t + 2) * kstep; const char* b2 = last ? nB : cB + (size_t)(t + 2) * kstep;
;             const char* a3 = a2 + kstep; const char* b3 = b2 + kstep;
;             if (last && has_next) S.a_ready(nxt);
;             if constexpr (SP2) {
;             PG8_LDB(B0, 0, 0); PG8_LDB(B1, 0, 1); PG8_SCHED; PG8_LDA(At, 0, 0); PG8_STAGE(PG8_SA(1, 1), a1 + hstep, voffA);
;             PG8_WAIT_V(8); PG8_WAIT_L(0); PG8_BAR; PG8_MMA(0, 0, At, B0); PG8_MMA(0, 1, At, B1); PG8_BAR; PG8_SCHED;
;     ...
; #pragma unroll
;         for (int a = 0; a < 2; ++a)
; #pragma unroll
;             for (int b = 0; b < 2; ++b)
; #pragma unroll
;                 for (int m = 0; m < 4; ++m)
; #pragma unroll
;                     for (int n = 0; n < 2; ++n) acc[a][b][m][n] = (f32x4){0.f, 0.f, 0.f, 0.f};
;         cur = nxt; cA = nA; cB = nB; ++ui;
.LBB0_382:
	s_lshl_b32 s46, s46, 8
	s_ashr_i32 s47, s46, 31
	s_lshl_b32 s48, s20, 8
	s_ashr_i32 s49, s48, 31
	s_lshl_b64 s[50:51], s[46:47], 11
	s_add_u32 s47, s30, s50
	s_addc_u32 s52, s31, s51
	s_lshl_b64 s[50:51], s[48:49], 1
	s_add_u32 s50, s47, s50
	s_addc_u32 s51, s52, s51
	s_add_u32 s52, s50, 0x40000
	s_addc_u32 s53, s51, 0
	s_add_u32 s47, s54, 0x100
	s_addc_u32 s49, s55, 0
	s_add_u32 s54, s44, 0x80
	s_addc_u32 s55, s45, 0
	v_mov_b32_e32 v0, 0
	v_lshl_add_u64 v[130:131], s[54:55], 0, v[180:181]
	v_lshl_add_u64 v[132:133], s[54:55], 0, v[182:183]
	s_mov_b32 s56, 0
	s_mov_b64 s[54:55], 0
	s_waitcnt lgkmcnt(0)
	v_mov_b32_e32 v1, v0
	v_mov_b32_e32 v2, v0
	v_mov_b32_e32 v3, v0
	v_mov_b32_e32 v4, v0
	v_mov_b32_e32 v5, v0
	v_mov_b32_e32 v6, v0
	v_mov_b32_e32 v7, v0
	v_mov_b32_e32 v16, v0
	v_mov_b32_e32 v17, v0
	v_mov_b32_e32 v18, v0
	v_mov_b32_e32 v19, v0
	v_mov_b32_e32 v20, v0
	v_mov_b32_e32 v21, v0
	v_mov_b32_e32 v22, v0
	v_mov_b32_e32 v23, v0
	v_mov_b32_e32 v32, v0
	v_mov_b32_e32 v33, v0
	v_mov_b32_e32 v34, v0
	v_mov_b32_e32 v35, v0
	v_mov_b32_e32 v36, v0
	v_mov_b32_e32 v37, v0
	v_mov_b32_e32 v38, v0
	v_mov_b32_e32 v39, v0
	v_mov_b32_e32 v48, v0
	v_mov_b32_e32 v49, v0
	v_mov_b32_e32 v50, v0
	v_mov_b32_e32 v51, v0
	v_mov_b32_e32 v52, v0
	v_mov_b32_e32 v53, v0
	v_mov_b32_e32 v54, v0
	v_mov_b32_e32 v55, v0
	v_mov_b32_e32 v8, v0
	v_mov_b32_e32 v9, v0
	v_mov_b32_e32 v10, v0
	v_mov_b32_e32 v11, v0
	v_mov_b32_e32 v12, v0
	v_mov_b32_e32 v13, v0
	v_mov_b32_e32 v14, v0
	v_mov_b32_e32 v15, v0
	v_mov_b32_e32 v24, v0
	v_mov_b32_e32 v25, v0
	v_mov_b32_e32 v26, v0
	v_mov_b32_e32 v27, v0
	v_mov_b32_e32 v28, v0
	v_mov_b32_e32 v29, v0
	v_mov_b32_e32 v30, v0
	v_mov_b32_e32 v31, v0
	v_mov_b32_e32 v40, v0
	v_mov_b32_e32 v41, v0
	v_mov_b32_e32 v42, v0
	v_mov_b32_e32 v43, v0
	v_mov_b32_e32 v44, v0
	v_mov_b32_e32 v45, v0
	v_mov_b32_e32 v46, v0
	v_mov_b32_e32 v47, v0
	v_mov_b32_e32 v56, v0
	v_mov_b32_e32 v57, v0
	v_mov_b32_e32 v58, v0
	v_mov_b32_e32 v59, v0
	v_mov_b32_e32 v60, v0
	v_mov_b32_e32 v61, v0
	v_mov_b32_e32 v62, v0
	v_mov_b32_e32 v63, v0
	v_mov_b32_e32 v64, v0
	v_mov_b32_e32 v65, v0
	v_mov_b32_e32 v66, v0
	v_mov_b32_e32 v67, v0
	v_mov_b32_e32 v68, v0
	v_mov_b32_e32 v69, v0
	v_mov_b32_e32 v70, v0
	v_mov_b32_e32 v71, v0
	v_mov_b32_e32 v82, v0
	v_mov_b32_e32 v83, v0
	v_mov_b32_e32 v84, v0
	v_mov_b32_e32 v85, v0
	v_mov_b32_e32 v86, v0
	v_mov_b32_e32 v87, v0
	v_mov_b32_e32 v88, v0
	v_mov_b32_e32 v89, v0
	v_mov_b32_e32 v98, v0
	v_mov_b32_e32 v99, v0
	v_mov_b32_e32 v100, v0
	v_mov_b32_e32 v101, v0
	v_mov_b32_e32 v102, v0
	v_mov_b32_e32 v103, v0
	v_mov_b32_e32 v104, v0
	v_mov_b32_e32 v105, v0
	v_mov_b32_e32 v114, v0
	v_mov_b32_e32 v115, v0
	v_mov_b32_e32 v116, v0
	v_mov_b32_e32 v117, v0
	v_mov_b32_e32 v118, v0
	v_mov_b32_e32 v119, v0
	v_mov_b32_e32 v120, v0
	v_mov_b32_e32 v121, v0
	v_mov_b32_e32 v72, v0
	v_mov_b32_e32 v73, v0
	v_mov_b32_e32 v74, v0
	v_mov_b32_e32 v75, v0
	v_mov_b32_e32 v76, v0
	v_mov_b32_e32 v77, v0
	v_mov_b32_e32 v78, v0
	v_mov_b32_e32 v79, v0
	v_mov_b32_e32 v90, v0
	v_mov_b32_e32 v91, v0
	v_mov_b32_e32 v92, v0
	v_mov_b32_e32 v93, v0
	v_mov_b32_e32 v94, v0
	v_mov_b32_e32 v95, v0
	v_mov_b32_e32 v96, v0
	v_mov_b32_e32 v97, v0
	v_mov_b32_e32 v106, v0
	v_mov_b32_e32 v107, v0
	v_mov_b32_e32 v108, v0
	v_mov_b32_e32 v109, v0
	v_mov_b32_e32 v110, v0
	v_mov_b32_e32 v111, v0
	v_mov_b32_e32 v112, v0
	v_mov_b32_e32 v113, v0
	v_mov_b32_e32 v122, v0
	v_mov_b32_e32 v123, v0
	v_mov_b32_e32 v124, v0
	v_mov_b32_e32 v125, v0
	v_mov_b32_e32 v126, v0
	v_mov_b32_e32 v127, v0
	v_mov_b32_e32 v128, v0
	v_mov_b32_e32 v129, v0
	v_readfirstlane_b32 s100, v202
	s_nop 3
	s_lshr_b32 s100, s100, 8
	s_cmp_eq_u32 s100, 0
	s_cbranch_scc1 .Lsp_op
	s_setprio 1
.Lsp_op:
	s_branch .LBB0_384
.LBB0_383:
	s_add_i32 s73, s56, 2
	s_add_u32 s57, s44, s54
	s_addc_u32 s74, s45, s55
	s_add_u32 s75, s57, 0x100
	s_addc_u32 s57, s74, 0
	s_add_u32 s74, s47, s54
	s_addc_u32 s76, s49, s55
	s_add_i32 s77, 0, 0x10000
	s_cmp_eq_u32 s15, s56
	s_cselect_b32 s57, s5, s57
	s_cselect_b32 s56, s4, s75
	s_cselect_b32 s75, s43, s76
	s_cselect_b32 s74, s42, s74
	s_add_i32 s76, 0, 0x14000
	v_add_u32_e32 v146, s77, v209
	v_add_u32_e32 v188, s76, v209
	ds_read_b128 v[134:137], v146
	ds_read_b128 v[138:141], v146 offset:1024
	ds_read_b128 v[142:145], v146 offset:2048
	ds_read_b128 v[146:149], v146 offset:3072
	ds_read_b128 v[150:153], v188
	ds_read_b128 v[154:157], v188 offset:1024
	ds_read_b128 v[184:187], v188 offset:2048
	ds_read_b128 v[188:191], v188 offset:3072
	v_lshl_add_u64 v[200:201], v[130:131], 0, s[54:55]
	s_add_i32 m0, s58, 0xc000
	ds_read_b128 v[192:195], v211
	ds_read_b128 v[196:199], v211 offset:1024
	ds_read_b128 v[212:215], v211 offset:2048
	ds_read_b128 v[216:219], v211 offset:3072
	ds_read_b128 v[220:223], v211 offset:4096
	ds_read_b128 v[224:227], v211 offset:5120
	ds_read_b128 v[228:231], v211 offset:6144
	ds_read_b128 v[232:235], v211 offset:7168
	global_load_lds_dwordx4 v[200:201], off
	v_lshl_add_u64 v[200:201], v[132:133], 0, s[54:55]
	s_add_i32 m0, s58, 0xe000
	s_nop 0
	global_load_lds_dwordx4 v[200:201], off
	s_waitcnt vmcnt(8)
	s_waitcnt lgkmcnt(0)
	s_barrier
; #define PG8_STAGE(bufoff, gbase, voff) do { _Pragma("unroll") for (int _i = 0; _i < 2; ++_i) \
;         __builtin_amdgcn_global_load_lds((const unsigned*)((const char*)(gbase) + (voff)[_i]), (PG8_LAS unsigned*)(lds + (bufoff) + ldsw + _i * 8192), 16, 0, 0); } while (0)
; #define PG8_LDA(dst, b, h) do { _Pragma("unroll") for (int m = 0; m < 4; ++m) _Pragma("unroll") for (int k = 0; k < 2; ++k) dst[m][k] = *(const PG8_LAS bf16x8*)(lds + PG8_SA(b, h) + aoff + m * 2048 + k * 1024); } while (0)
; #define PG8_MMA(ai, bj, At, Bt) do { __builtin_amdgcn_s_setprio(1); _Pragma("unroll") for (int m = 0; m < 4; ++m) _Pragma("unroll") for (int n = 0; n < 2; ++n) _Pragma("unroll") for (int k = 0; k < 2; ++k) \
;         acc[ai][bj][m][n] = __builtin_amdgcn_mfma_f32_16x16x32_bf16(Bt[n][k], At[m][k], acc[ai][bj][m][n], 0, 0, 0); __builtin_amdgcn_s_setprio(0); } while (0)
; #define PG8_WAIT_V(n) asm volatile("s_waitcnt vmcnt(" #n ")" ::: "memory")
; #define PG8_WAIT_L(n) asm volatile("s_waitcnt lgkmcnt(" #n ")" ::: "memory")
; #define PG8_BAR __builtin_amdgcn_s_barrier()
; #define PG8_SCHED __builtin_amdgcn_sched_barrier(0)
; template <class Epi, class Sched, bool ALIGN_EPI = false, bool SP2 = false>
; __device__ __forceinline__ void gemm_phase(PG8_LAS unsigned char* lds, const Gemm g, const Sched& S, const Epi& E) {
;     ...
;             PG8_WAIT_V(8); PG8_WAIT_L(0); PG8_BAR; PG8_MMA(0, 0, At, B0); PG8_MMA(0, 1, At, B1); PG8_BAR; PG8_SCHED;
;             PG8_LDA(At, 0, 1); PG8_STAGE(PG8_SB(0, 0), b2, voffB); PG8_STAGE(PG8_SB(0, 1), b2 + hstep, voffB); PG8_STAGE(PG8_SA(0, 0), a2, voffA);
;             PG8_WAIT_V(8); PG8_WAIT_L(0); PG8_BAR; PG8_MMA(1, 0, At, B0); PG8_MMA(1, 1, At, B1); PG8_BAR; PG8_SCHED;
	v_mfma_f32_16x16x32_bf16 v[126:129], v[134:137], v[192:195], v[126:129]
	v_mfma_f32_16x16x32_bf16 v[122:125], v[142:145], v[192:195], v[122:125]
	v_mfma_f32_16x16x32_bf16 v[110:113], v[134:137], v[212:215], v[110:113]
	v_mfma_f32_16x16x32_bf16 v[106:109], v[142:145], v[212:215], v[106:109]
	v_mfma_f32_16x16x32_bf16 v[94:97], v[134:137], v[220:223], v[94:97]
	v_mfma_f32_16x16x32_bf16 v[90:93], v[142:145], v[220:223], v[90:93]
	v_mfma_f32_16x16x32_bf16 v[76:79], v[134:137], v[228:231], v[76:79]
	v_mfma_f32_16x16x32_bf16 v[72:75], v[142:145], v[228:231], v[72:75]
	v_mfma_f32_16x16x32_bf16 v[126:129], v[138:141], v[196:199], v[126:129]
	v_mfma_f32_16x16x32_bf16 v[122:125], v[146:149], v[196:199], v[122:125]
	v_mfma_f32_16x16x32_bf16 v[110:113], v[138:141], v[216:219], v[110:113]
	v_mfma_f32_16x16x32_bf16 v[106:109], v[146:149], v[216:219], v[106:109]
	v_mfma_f32_16x16x32_bf16 v[94:97], v[138:141], v[224:227], v[94:97]
	v_mfma_f32_16x16x32_bf16 v[90:93], v[146:149], v[224:227], v[90:93]
	v_mfma_f32_16x16x32_bf16 v[76:79], v[138:141], v[232:235], v[76:79]
	v_mfma_f32_16x16x32_bf16 v[72:75], v[146:149], v[232:235], v[72:75]
	v_mfma_f32_16x16x32_bf16 v[118:121], v[150:153], v[192:195], v[118:121]
	v_mfma_f32_16x16x32_bf16 v[114:117], v[184:187], v[192:195], v[114:117]
	v_mfma_f32_16x16x32_bf16 v[102:105], v[150:153], v[212:215], v[102:105]
	v_mfma_f32_16x16x32_bf16 v[98:101], v[184:187], v[212:215], v[98:101]
	v_mfma_f32_16x16x32_bf16 v[86:89], v[150:153], v[220:223], v[86:89]
	v_mfma_f32_16x16x32_bf16 v[82:85], v[184:187], v[220:223], v[82:85]
	v_mfma_f32_16x16x32_bf16 v[68:71], v[150:153], v[228:231], v[68:71]
	v_mfma_f32_16x16x32_bf16 v[64:67], v[184:187], v[228:231], v[64:67]
	v_mfma_f32_16x16x32_bf16 v[118:121], v[154:157], v[196:199], v[118:121]
	v_mfma_f32_16x16x32_bf16 v[114:117], v[188:191], v[196:199], v[114:117]
	v_mfma_f32_16x16x32_bf16 v[102:105], v[154:157], v[216:219], v[102:105]
	v_mfma_f32_16x16x32_bf16 v[98:101], v[188:191], v[216:219], v[98:101]
	v_mfma_f32_16x16x32_bf16 v[86:89], v[154:157], v[224:227], v[86:89]
	v_mfma_f32_16x16x32_bf16 v[82:85], v[188:191], v[224:227], v[82:85]
	v_mfma_f32_16x16x32_bf16 v[68:71], v[154:157], v[232:235], v[68:71]
	v_mfma_f32_16x16x32_bf16 v[64:67], v[188:191], v[232:235], v[64:67]
	s_barrier
	s_add_i32 s77, s77, s39
	v_lshl_add_u64 v[200:201], s[74:75], 0, v[176:177]
	s_mov_b32 m0, s77
	ds_read_b128 v[192:195], v211 offset:16384
	ds_read_b128 v[196:199], v211 offset:17408
	ds_read_b128 v[212:215], v211 offset:18432
	ds_read_b128 v[216:219], v211 offset:19456
	ds_read_b128 v[220:223], v211 offset:20480
	ds_read_b128 v[224:227], v211 offset:21504
	ds_read_b128 v[228:231], v211 offset:22528
	ds_read_b128 v[232:235], v211 offset:23552
	global_load_lds_dwordx4 v[200:201], off
	s_add_i32 m0, s77, 0x2000
	v_lshl_add_u64 v[236:237], s[74:75], 0, v[158:159]
	s_add_u32 s74, s74, s14
	s_addc_u32 s75, s75, 0
	s_add_i32 s76, s76, s39
	global_load_lds_dwordx4 v[236:237], off
	v_lshl_add_u64 v[238:239], s[74:75], 0, v[176:177]
	s_mov_b32 m0, s76
	v_lshl_add_u64 v[240:241], s[74:75], 0, v[158:159]
	global_load_lds_dwordx4 v[238:239], off
	s_add_i32 m0, s76, 0x2000
	v_lshl_add_u64 v[242:243], s[56:57], 0, v[178:179]
	global_load_lds_dwordx4 v[240:241], off
	s_mov_b32 m0, s58
	v_lshl_add_u64 v[244:245], s[56:57], 0, v[160:161]
	global_load_lds_dwordx4 v[242:243], off
	s_mov_b32 m0, s59
	s_nop 0
	global_load_lds_dwordx4 v[244:245], off
	s_waitcnt vmcnt(8)
	s_waitcnt lgkmcnt(0)
	s_barrier
	v_mfma_f32_16x16x32_bf16 v[60:63], v[134:137], v[192:195], v[60:63]
	v_mfma_f32_16x16x32_bf16 v[56:59], v[142:145], v[192:195], v[56:59]
	v_mfma_f32_16x16x32_bf16 v[44:47], v[134:137], v[212:215], v[44:47]
	v_mfma_f32_16x16x32_bf16 v[40:43], v[142:145], v[212:215], v[40:43]
	v_mfma_f32_16x16x32_bf16 v[28:31], v[134:137], v[220:223], v[28:31]
	v_mfma_f32_16x16x32_bf16 v[24:27], v[142:145], v[220:223], v[24:27]
	v_mfma_f32_16x16x32_bf16 v[12:15], v[134:137], v[228:231], v[12:15]
	v_mfma_f32_16x16x32_bf16 v[8:11], v[142:145], v[228:231], v[8:11]
	v_mfma_f32_16x16x32_bf16 v[60:63], v[138:141], v[196:199], v[60:63]
	v_mfma_f32_16x16x32_bf16 v[56:59], v[146:149], v[196:199], v[56:59]
	v_mfma_f32_16x16x32_bf16 v[44:47], v[138:141], v[216:219], v[44:47]
	v_mfma_f32_16x16x32_bf16 v[40:43], v[146:149], v[216:219], v[40:43]
	v_mfma_f32_16x16x32_bf16 v[28:31], v[138:141], v[224:227], v[28:31]
	v_mfma_f32_16x16x32_bf16 v[24:27], v[146:149], v[224:227], v[24:27]
	v_mfma_f32_16x16x32_bf16 v[12:15], v[138:141], v[232:235], v[12:15]
	v_mfma_f32_16x16x32_bf16 v[8:11], v[146:149], v[232:235], v[8:11]
	v_mfma_f32_16x16x32_bf16 v[52:55], v[150:153], v[192:195], v[52:55]
	v_mfma_f32_16x16x32_bf16 v[48:51], v[184:187], v[192:195], v[48:51]
	v_mfma_f32_16x16x32_bf16 v[36:39], v[150:153], v[212:215], v[36:39]
	v_mfma_f32_16x16x32_bf16 v[32:35], v[184:187], v[212:215], v[32:35]
	v_mfma_f32_16x16x32_bf16 v[20:23], v[150:153], v[220:223], v[20:23]
	v_mfma_f32_16x16x32_bf16 v[16:19], v[184:187], v[220:223], v[16:19]
	v_mfma_f32_16x16x32_bf16 v[4:7], v[150:153], v[228:231], v[4:7]
	v_mfma_f32_16x16x32_bf16 v[0:3], v[184:187], v[228:231], v[0:3]
	v_mfma_f32_16x16x32_bf16 v[52:55], v[154:157], v[196:199], v[52:55]
	v_mfma_f32_16x16x32_bf16 v[48:51], v[188:191], v[196:199], v[48:51]
	v_mfma_f32_16x16x32_bf16 v[36:39], v[154:157], v[216:219], v[36:39]
	v_mfma_f32_16x16x32_bf16 v[32:35], v[188:191], v[216:219], v[32:35]
	v_mfma_f32_16x16x32_bf16 v[20:23], v[154:157], v[224:227], v[20:23]
	v_mfma_f32_16x16x32_bf16 v[16:19], v[188:191], v[224:227], v[16:19]
	v_mfma_f32_16x16x32_bf16 v[4:7], v[154:157], v[232:235], v[4:7]
	v_mfma_f32_16x16x32_bf16 v[0:3], v[188:191], v[232:235], v[0:3]
	s_barrier
; #define PG8_STAGE(bufoff, gbase, voff) do { _Pragma("unroll") for (int _i = 0; _i < 2; ++_i) \
;         __builtin_amdgcn_global_load_lds((const unsigned*)((const char*)(gbase) + (voff)[_i]), (PG8_LAS unsigned*)(lds + (bufoff) + ldsw + _i * 8192), 16, 0, 0); } while (0)
; #define PG8_LDA(dst, b, h) do { _Pragma("unroll") for (int m = 0; m < 4; ++m) _Pragma("unroll") for (int k = 0; k < 2; ++k) dst[m][k] = *(const PG8_LAS bf16x8*)(lds + PG8_SA(b, h) + aoff + m * 2048 + k * 1024); } while (0)
; #define PG8_LDB(dst, b, h) do { _Pragma("unroll") for (int n = 0; n < 2; ++n) _Pragma("unroll") for (int k = 0; k < 2; ++k) dst[n][k] = *(const PG8_LAS bf16x8*)(lds + PG8_SB(b, h) + boff + n * 2048 + k * 1024); } while (0)
; #define PG8_MMA(ai, bj, At, Bt) do { __builtin_amdgcn_s_setprio(1); _Pragma("unroll") for (int m = 0; m < 4; ++m) _Pragma("unroll") for (int n = 0; n < 2; ++n) _Pragma("unroll") for (int k = 0; k < 2; ++k) \
;         acc[ai][bj][m][n] = __builtin_amdgcn_mfma_f32_16x16x32_bf16(Bt[n][k], At[m][k], acc[ai][bj][m][n], 0, 0, 0); __builtin_amdgcn_s_setprio(0); } while (0)
; #define PG8_WAIT_V(n) asm volatile("s_waitcnt vmcnt(" #n ")" ::: "memory")
; #define PG8_WAIT_L(n) asm volatile("s_waitcnt lgkmcnt(" #n ")" ::: "memory")
; #define PG8_BAR __builtin_amdgcn_s_barrier()
; #define PG8_SCHED __builtin_amdgcn_sched_barrier(0)
; template <class Epi, class Sched, bool ALIGN_EPI = false, bool SP2 = false>
; __device__ __forceinline__ void gemm_phase(PG8_LAS unsigned char* lds, const Gemm g, const Sched& S, const Epi& E) {
;     ...
;             PG8_LDB(B0, 1, 0); PG8_LDB(B1, 1, 1); PG8_SCHED; PG8_LDA(At, 1, 0); PG8_STAGE(PG8_SA(0, 1), a2 + hstep, voffA);
;             PG8_WAIT_V(8); PG8_WAIT_L(0); PG8_BAR; PG8_MMA(0, 0, At, B0); PG8_MMA(0, 1, At, B1); PG8_BAR; PG8_SCHED;
;             PG8_LDA(At, 1, 1); PG8_STAGE(PG8_SB(1, 0), b3, voffB); PG8_STAGE(PG8_SB(1, 1), b3 + hstep, voffB); PG8_STAGE(PG8_SA(1, 0), a3, voffA);
;             PG8_WAIT_V(8); PG8_WAIT_L(0); PG8_BAR; PG8_MMA(1, 0, At, B0); PG8_MMA(1, 1, At, B1); PG8_BAR; PG8_SCHED;
	s_add_i32 s74, 0, 0x18000
	s_add_i32 s75, 0, 0x1c000
	v_add_u32_e32 v146, s74, v209
	v_add_u32_e32 v188, s75, v209
	ds_read_b128 v[134:137], v146
	ds_read_b128 v[138:141], v146 offset:1024
	ds_read_b128 v[142:145], v146 offset:2048
	ds_read_b128 v[146:149], v146 offset:3072
	ds_read_b128 v[150:153], v188
	ds_read_b128 v[154:157], v188 offset:1024
	ds_read_b128 v[184:187], v188 offset:2048
	ds_read_b128 v[188:191], v188 offset:3072
	s_add_u32 s56, s56, s14
	s_addc_u32 s57, s57, 0
	s_mov_b32 m0, s60
	v_lshl_add_u64 v[246:247], s[56:57], 0, v[178:179]
	ds_read_b128 v[192:195], v211 offset:32768
	ds_read_b128 v[196:199], v211 offset:33792
	ds_read_b128 v[212:215], v211 offset:34816
	ds_read_b128 v[216:219], v211 offset:35840
	ds_read_b128 v[220:223], v211 offset:36864
	ds_read_b128 v[224:227], v211 offset:37888
	ds_read_b128 v[228:231], v211 offset:38912
	ds_read_b128 v[232:235], v211 offset:39936
	global_load_lds_dwordx4 v[246:247], off
	v_lshl_add_u64 v[246:247], s[56:57], 0, v[160:161]
	s_mov_b32 m0, s61
	s_nop 0
	global_load_lds_dwordx4 v[246:247], off
	s_waitcnt vmcnt(8)
	s_waitcnt lgkmcnt(0)
	s_barrier
	v_mfma_f32_16x16x32_bf16 v[126:129], v[134:137], v[192:195], v[126:129]
	v_mfma_f32_16x16x32_bf16 v[122:125], v[142:145], v[192:195], v[122:125]
	v_mfma_f32_16x16x32_bf16 v[110:113], v[134:137], v[212:215], v[110:113]
	v_mfma_f32_16x16x32_bf16 v[106:109], v[142:145], v[212:215], v[106:109]
	v_mfma_f32_16x16x32_bf16 v[94:97], v[134:137], v[220:223], v[94:97]
	v_mfma_f32_16x16x32_bf16 v[90:93], v[142:145], v[220:223], v[90:93]
	v_mfma_f32_16x16x32_bf16 v[76:79], v[134:137], v[228:231], v[76:79]
	v_mfma_f32_16x16x32_bf16 v[72:75], v[142:145], v[228:231], v[72:75]
	v_mfma_f32_16x16x32_bf16 v[126:129], v[138:141], v[196:199], v[126:129]
	v_mfma_f32_16x16x32_bf16 v[122:125], v[146:149], v[196:199], v[122:125]
	v_mfma_f32_16x16x32_bf16 v[110:113], v[138:141], v[216:219], v[110:113]
	v_mfma_f32_16x16x32_bf16 v[106:109], v[146:149], v[216:219], v[106:109]
	v_mfma_f32_16x16x32_bf16 v[94:97], v[138:141], v[224:227], v[94:97]
	v_mfma_f32_16x16x32_bf16 v[90:93], v[146:149], v[224:227], v[90:93]
	v_mfma_f32_16x16x32_bf16 v[76:79], v[138:141], v[232:235], v[76:79]
	v_mfma_f32_16x16x32_bf16 v[72:75], v[146:149], v[232:235], v[72:75]
	v_mfma_f32_16x16x32_bf16 v[118:121], v[150:153], v[192:195], v[118:121]
	v_mfma_f32_16x16x32_bf16 v[114:117], v[184:187], v[192:195], v[114:117]
	v_mfma_f32_16x16x32_bf16 v[102:105], v[150:153], v[212:215], v[102:105]
	v_mfma_f32_16x16x32_bf16 v[98:101], v[184:187], v[212:215], v[98:101]
	v_mfma_f32_16x16x32_bf16 v[86:89], v[150:153], v[220:223], v[86:89]
	v_mfma_f32_16x16x32_bf16 v[82:85], v[184:187], v[220:223], v[82:85]
	v_mfma_f32_16x16x32_bf16 v[68:71], v[150:153], v[228:231], v[68:71]
	v_mfma_f32_16x16x32_bf16 v[64:67], v[184:187], v[228:231], v[64:67]
	v_mfma_f32_16x16x32_bf16 v[118:121], v[154:157], v[196:199], v[118:121]
	v_mfma_f32_16x16x32_bf16 v[114:117], v[188:191], v[196:199], v[114:117]
	v_mfma_f32_16x16x32_bf16 v[102:105], v[154:157], v[216:219], v[102:105]
	v_mfma_f32_16x16x32_bf16 v[98:101], v[188:191], v[216:219], v[98:101]
	v_mfma_f32_16x16x32_bf16 v[86:89], v[154:157], v[224:227], v[86:89]
	v_mfma_f32_16x16x32_bf16 v[82:85], v[188:191], v[224:227], v[82:85]
	v_mfma_f32_16x16x32_bf16 v[68:71], v[154:157], v[232:235], v[68:71]
	v_mfma_f32_16x16x32_bf16 v[64:67], v[188:191], v[232:235], v[64:67]
	s_barrier
	s_add_i32 s56, s74, s39
	v_lshl_add_u64 v[200:201], v[200:201], 0, s[40:41]
	s_mov_b32 m0, s56
	ds_read_b128 v[192:195], v211 offset:49152
	ds_read_b128 v[196:199], v211 offset:50176
	ds_read_b128 v[212:215], v211 offset:51200
	ds_read_b128 v[216:219], v211 offset:52224
	ds_read_b128 v[220:223], v211 offset:53248
	ds_read_b128 v[224:227], v211 offset:54272
	ds_read_b128 v[228:231], v211 offset:55296
	ds_read_b128 v[232:235], v211 offset:56320
	global_load_lds_dwordx4 v[200:201], off
	v_lshl_add_u64 v[200:201], v[236:237], 0, s[40:41]
	s_add_i32 m0, s56, 0x2000
	s_add_i32 s56, s75, s39
	global_load_lds_dwordx4 v[200:201], off
	v_lshl_add_u64 v[200:201], v[238:239], 0, s[40:41]
	s_mov_b32 m0, s56
	s_nop 0
	global_load_lds_dwordx4 v[200:201], off
	v_lshl_add_u64 v[200:201], v[240:241], 0, s[40:41]
	s_add_i32 m0, s56, 0x2000
	s_nop 0
	global_load_lds_dwordx4 v[200:201], off
	v_lshl_add_u64 v[200:201], v[242:243], 0, s[40:41]
	s_mov_b32 m0, s66
	s_nop 0
	global_load_lds_dwordx4 v[200:201], off
	v_lshl_add_u64 v[200:201], v[244:245], 0, s[40:41]
	s_mov_b32 m0, s67
	s_nop 0
	global_load_lds_dwordx4 v[200:201], off
	s_waitcnt vmcnt(8)
	s_waitcnt lgkmcnt(0)
	s_barrier
	v_mfma_f32_16x16x32_bf16 v[60:63], v[134:137], v[192:195], v[60:63]
	v_mfma_f32_16x16x32_bf16 v[56:59], v[142:145], v[192:195], v[56:59]
	v_mfma_f32_16x16x32_bf16 v[44:47], v[134:137], v[212:215], v[44:47]
	v_mfma_f32_16x16x32_bf16 v[40:43], v[142:145], v[212:215], v[40:43]
	v_mfma_f32_16x16x32_bf16 v[28:31], v[134:137], v[220:223], v[28:31]
	v_mfma_f32_16x16x32_bf16 v[24:27], v[142:145], v[220:223], v[24:27]
	v_mfma_f32_16x16x32_bf16 v[12:15], v[134:137], v[228:231], v[12:15]
	v_mfma_f32_16x16x32_bf16 v[8:11], v[142:145], v[228:231], v[8:11]
	v_mfma_f32_16x16x32_bf16 v[60:63], v[138:141], v[196:199], v[60:63]
	v_mfma_f32_16x16x32_bf16 v[56:59], v[146:149], v[196:199], v[56:59]
	v_mfma_f32_16x16x32_bf16 v[44:47], v[138:141], v[216:219], v[44:47]
	v_mfma_f32_16x16x32_bf16 v[40:43], v[146:149], v[216:219], v[40:43]
	v_mfma_f32_16x16x32_bf16 v[28:31], v[138:141], v[224:227], v[28:31]
	v_mfma_f32_16x16x32_bf16 v[24:27], v[146:149], v[224:227], v[24:27]
	v_mfma_f32_16x16x32_bf16 v[12:15], v[138:141], v[232:235], v[12:15]
	v_mfma_f32_16x16x32_bf16 v[8:11], v[146:149], v[232:235], v[8:11]
	v_mfma_f32_16x16x32_bf16 v[52:55], v[150:153], v[192:195], v[52:55]
	v_mfma_f32_16x16x32_bf16 v[48:51], v[184:187], v[192:195], v[48:51]
	v_mfma_f32_16x16x32_bf16 v[36:39], v[150:153], v[212:215], v[36:39]
	v_mfma_f32_16x16x32_bf16 v[32:35], v[184:187], v[212:215], v[32:35]
	v_mfma_f32_16x16x32_bf16 v[20:23], v[150:153], v[220:223], v[20:23]
	v_mfma_f32_16x16x32_bf16 v[16:19], v[184:187], v[220:223], v[16:19]
	v_mfma_f32_16x16x32_bf16 v[4:7], v[150:153], v[228:231], v[4:7]
	v_mfma_f32_16x16x32_bf16 v[0:3], v[184:187], v[228:231], v[0:3]
	v_mfma_f32_16x16x32_bf16 v[52:55], v[154:157], v[196:199], v[52:55]
	v_mfma_f32_16x16x32_bf16 v[48:51], v[188:191], v[196:199], v[48:51]
	v_mfma_f32_16x16x32_bf16 v[36:39], v[154:157], v[216:219], v[36:39]
	v_mfma_f32_16x16x32_bf16 v[32:35], v[188:191], v[216:219], v[32:35]
	v_mfma_f32_16x16x32_bf16 v[20:23], v[154:157], v[224:227], v[20:23]
	v_mfma_f32_16x16x32_bf16 v[16:19], v[188:191], v[224:227], v[16:19]
	v_mfma_f32_16x16x32_bf16 v[4:7], v[154:157], v[232:235], v[4:7]
	v_mfma_f32_16x16x32_bf16 v[0:3], v[188:191], v[232:235], v[0:3]
	s_barrier
	s_add_u32 s54, s54, 0x100
	s_addc_u32 s55, s55, 0
	s_cmp_ge_u32 s73, s63
	s_mov_b32 s56, s73
	s_cbranch_scc1 .LBB0_386

; #define PG8_BAR __builtin_amdgcn_s_barrier()
; template <class Epi, class Sched, bool ALIGN_EPI = false, bool SP2 = false>
; __device__ __forceinline__ void gemm_phase(PG8_LAS unsigned char* lds, const Gemm g, const Sched& S, const Epi& E) {
;     ...
;         }
;         if constexpr (ALIGN_EPI) { if (wr == 0) PG8_BAR; }
.LBB0_386:
	s_setprio 0
	s_and_b64 vcc, exec, s[18:19]
	s_cbranch_vccz .LBB0_388
	s_barrier
